# hand-off version with two extra s_setprio 0/1 dips per 32-MFMA block (after MFMA 8 and 24)
# speedup vs baseline: 1.0088x; 1.0088x over previous
; #define PG8_STAGE(bufoff, gbase, voff) do { _Pragma("unroll") for (int _i = 0; _i < 2; ++_i) \
;         __builtin_amdgcn_global_load_lds((const unsigned*)((const char*)(gbase) + (voff)[_i]), (LAS unsigned*)(lds + (bufoff) + ldsw + _i * 8192), 16, 0, 0); } while (0)
; #define PG8_LDA(dst, b, h) do { _Pragma("unroll") for (int m = 0; m < 4; ++m) _Pragma("unroll") for (int k = 0; k < 2; ++k) dst[m][k] = *(const LAS bf16x8*)(lds + PG8_SA(b, h) + aoff + m * 2048 + k * 1024); } while (0)
; #define PG8_LDB(dst, b, h) do { _Pragma("unroll") for (int n = 0; n < 2; ++n) _Pragma("unroll") for (int k = 0; k < 2; ++k) dst[n][k] = *(const LAS bf16x8*)(lds + PG8_SB(b, h) + boff + n * 2048 + k * 1024); } while (0)
; #define PG8_MMA(ai, bj, At, Bt) do { __builtin_amdgcn_s_setprio(1); _Pragma("unroll") for (int m = 0; m < 4; ++m) _Pragma("unroll") for (int n = 0; n < 2; ++n) _Pragma("unroll") for (int k = 0; k < 2; ++k) \
;         acc[ai][bj][m][n] = __builtin_amdgcn_mfma_f32_16x16x32_bf16(Bt[n][k], At[m][k], acc[ai][bj][m][n], 0, 0, 0); __builtin_amdgcn_s_setprio(0); } while (0)
; #define PG8_WAIT_V(n) asm volatile("s_waitcnt vmcnt(" #n ")" ::: "memory")
; #define PG8_WAIT_L(n) asm volatile("s_waitcnt lgkmcnt(" #n ")" ::: "memory")
; #define PG8_BAR __builtin_amdgcn_s_barrier()
; #define PG8_SCHED __builtin_amdgcn_sched_barrier(0)
; template <class Epi, class Sched>
; __device__ __forceinline__ void gemm_phase(LAS unsigned char* lds, const int K, const Sched& S, const Epi& E) {
;     ...
;         for (int t = 0; t < nt; t += 2) {
;             const bool last = (t == nt - 2);
;             const char* a1 = cA + (size_t)(t + 1) * kstep;
;             const char* a2 = last ? nA : cA + (size_t)(t + 2) * kstep; const char* b2 = last ? nB : cB + (size_t)(t + 2) * kstep;
;             const char* a3 = a2 + kstep; const char* b3 = b2 + kstep;
;             PG8_LDB(B0, 0, 0); PG8_LDB(B1, 0, 1); PG8_SCHED; PG8_LDA(At, 0, 0); PG8_STAGE(PG8_SA(1, 1), a1 + hstep, voffA);
;             PG8_WAIT_V(8); PG8_WAIT_L(0); PG8_BAR; PG8_MMA(0, 0, At, B0); PG8_MMA(0, 1, At, B1); PG8_BAR; PG8_SCHED;
;             PG8_LDA(At, 0, 1); PG8_STAGE(PG8_SB(0, 0), b2, voffB); PG8_STAGE(PG8_SB(0, 1), b2 + hstep, voffB); PG8_STAGE(PG8_SA(0, 0), a2, voffA);
;             PG8_WAIT_V(8); PG8_WAIT_L(0); PG8_BAR; PG8_MMA(1, 0, At, B0); PG8_MMA(1, 1, At, B1); PG8_BAR; PG8_SCHED;
.LBB0_403:
	s_add_u32 s14, s8, 0xfffc0080
	s_addc_u32 s15, s9, -1
	s_add_i32 s16, 0, 0x10000
	s_cmp_eq_u32 s13, 12
	s_cselect_b32 s55, s2, s15
	s_cselect_b32 s54, s4, s14
	v_add_u32_e32 v128, s16, v149
	s_cselect_b32 s39, s5, s12
	s_cselect_b32 s38, s10, s11
	s_add_i32 s17, 0, 0x14000
	ds_read_b128 v[158:161], v128
	ds_read_b128 v[162:165], v128 offset:1024
	ds_read_b128 v[184:187], v128 offset:2048
	ds_read_b128 v[188:191], v128 offset:3072
	v_add_u32_e32 v128, s17, v149
	ds_read_b128 v[192:195], v128
	ds_read_b128 v[196:199], v128 offset:1024
	ds_read_b128 v[200:203], v128 offset:2048
	ds_read_b128 v[204:207], v128 offset:3072
	v_lshl_add_u64 v[166:167], s[8:9], 0, v[154:155]
	s_add_i32 m0, s59, 0xc000
	ds_read_b128 v[208:211], v147
	ds_read_b128 v[212:215], v147 offset:1024
	ds_read_b128 v[216:219], v147 offset:2048
	ds_read_b128 v[220:223], v147 offset:3072
	ds_read_b128 v[224:227], v147 offset:4096
	ds_read_b128 v[228:231], v147 offset:5120
	ds_read_b128 v[232:235], v147 offset:6144
	ds_read_b128 v[236:239], v147 offset:7168
	global_load_lds_dwordx4 v[166:167], off
	v_lshl_add_u64 v[166:167], s[8:9], 0, v[156:157]
	s_add_i32 m0, s59, 0xe000
	s_nop 0
	global_load_lds_dwordx4 v[166:167], off
	s_waitcnt vmcnt(8)
	s_waitcnt lgkmcnt(0)
	s_setprio 1
	s_barrier
	v_mfma_f32_16x16x32_bf16 v[124:127], v[158:161], v[208:211], v[124:127]
	v_mfma_f32_16x16x32_bf16 v[120:123], v[184:187], v[208:211], v[120:123]
	v_mfma_f32_16x16x32_bf16 v[108:111], v[158:161], v[216:219], v[108:111]
	v_mfma_f32_16x16x32_bf16 v[104:107], v[184:187], v[216:219], v[104:107]
	v_mfma_f32_16x16x32_bf16 v[92:95], v[158:161], v[224:227], v[92:95]
	v_mfma_f32_16x16x32_bf16 v[88:91], v[184:187], v[224:227], v[88:91]
	v_mfma_f32_16x16x32_bf16 v[76:79], v[158:161], v[232:235], v[76:79]
	v_mfma_f32_16x16x32_bf16 v[72:75], v[184:187], v[232:235], v[72:75]
	s_setprio 0
	s_setprio 1
	v_mfma_f32_16x16x32_bf16 v[124:127], v[162:165], v[212:215], v[124:127]
	v_mfma_f32_16x16x32_bf16 v[120:123], v[188:191], v[212:215], v[120:123]
	v_mfma_f32_16x16x32_bf16 v[108:111], v[162:165], v[220:223], v[108:111]
	v_mfma_f32_16x16x32_bf16 v[104:107], v[188:191], v[220:223], v[104:107]
	v_mfma_f32_16x16x32_bf16 v[92:95], v[162:165], v[228:231], v[92:95]
	v_mfma_f32_16x16x32_bf16 v[88:91], v[188:191], v[228:231], v[88:91]
	v_mfma_f32_16x16x32_bf16 v[76:79], v[162:165], v[236:239], v[76:79]
	v_mfma_f32_16x16x32_bf16 v[72:75], v[188:191], v[236:239], v[72:75]
	s_setprio 0
	s_setprio 1
	v_mfma_f32_16x16x32_bf16 v[116:119], v[192:195], v[208:211], v[116:119]
	v_mfma_f32_16x16x32_bf16 v[112:115], v[200:203], v[208:211], v[112:115]
	v_mfma_f32_16x16x32_bf16 v[100:103], v[192:195], v[216:219], v[100:103]
	v_mfma_f32_16x16x32_bf16 v[96:99], v[200:203], v[216:219], v[96:99]
	v_mfma_f32_16x16x32_bf16 v[84:87], v[192:195], v[224:227], v[84:87]
	v_mfma_f32_16x16x32_bf16 v[80:83], v[200:203], v[224:227], v[80:83]
	v_mfma_f32_16x16x32_bf16 v[68:71], v[192:195], v[232:235], v[68:71]
	v_mfma_f32_16x16x32_bf16 v[64:67], v[200:203], v[232:235], v[64:67]
	s_setprio 0
	s_setprio 1
	v_mfma_f32_16x16x32_bf16 v[116:119], v[196:199], v[212:215], v[116:119]
	v_mfma_f32_16x16x32_bf16 v[112:115], v[204:207], v[212:215], v[112:115]
	v_mfma_f32_16x16x32_bf16 v[100:103], v[196:199], v[220:223], v[100:103]
	v_mfma_f32_16x16x32_bf16 v[96:99], v[204:207], v[220:223], v[96:99]
	v_mfma_f32_16x16x32_bf16 v[84:87], v[196:199], v[228:231], v[84:87]
	v_mfma_f32_16x16x32_bf16 v[80:83], v[204:207], v[228:231], v[80:83]
	v_mfma_f32_16x16x32_bf16 v[68:71], v[196:199], v[236:239], v[68:71]
	v_mfma_f32_16x16x32_bf16 v[64:67], v[204:207], v[236:239], v[64:67]
	s_barrier
	s_setprio 0
	s_add_i32 s14, s16, s58
	v_lshl_add_u64 v[166:167], s[38:39], 0, v[140:141]
	s_mov_b32 m0, s14
	ds_read_b128 v[208:211], v147 offset:16384
	ds_read_b128 v[212:215], v147 offset:17408
	ds_read_b128 v[216:219], v147 offset:18432
	ds_read_b128 v[220:223], v147 offset:19456
	ds_read_b128 v[224:227], v147 offset:20480
	ds_read_b128 v[228:231], v147 offset:21504
	ds_read_b128 v[232:235], v147 offset:22528
	ds_read_b128 v[236:239], v147 offset:23552
	global_load_lds_dwordx4 v[166:167], off
	s_add_i32 m0, s14, 0x2000
	s_add_u32 s14, s38, 0x40000
	v_lshl_add_u64 v[180:181], s[38:39], 0, v[144:145]
	s_addc_u32 s15, s39, 0
	s_add_i32 s16, s17, s58
	global_load_lds_dwordx4 v[180:181], off
	v_lshl_add_u64 v[182:183], s[14:15], 0, v[140:141]
	s_mov_b32 m0, s16
	v_lshl_add_u64 v[240:241], s[54:55], 0, v[142:143]
	global_load_lds_dwordx4 v[182:183], off
	v_lshl_add_u64 v[182:183], s[14:15], 0, v[144:145]
	s_add_i32 m0, s16, 0x2000
	s_nop 0
	global_load_lds_dwordx4 v[182:183], off
	v_lshl_add_u64 v[182:183], s[54:55], 0, v[138:139]
	s_mov_b32 m0, s59
	s_nop 0
	global_load_lds_dwordx4 v[182:183], off
	s_mov_b32 m0, s60
	s_nop 0
	global_load_lds_dwordx4 v[240:241], off
	s_waitcnt vmcnt(8)
	s_waitcnt lgkmcnt(0)
	s_setprio 1
	s_barrier
; #define PG8_STAGE(bufoff, gbase, voff) do { _Pragma("unroll") for (int _i = 0; _i < 2; ++_i) \
;         __builtin_amdgcn_global_load_lds((const unsigned*)((const char*)(gbase) + (voff)[_i]), (LAS unsigned*)(lds + (bufoff) + ldsw + _i * 8192), 16, 0, 0); } while (0)
; #define PG8_LDA(dst, b, h) do { _Pragma("unroll") for (int m = 0; m < 4; ++m) _Pragma("unroll") for (int k = 0; k < 2; ++k) dst[m][k] = *(const LAS bf16x8*)(lds + PG8_SA(b, h) + aoff + m * 2048 + k * 1024); } while (0)
; #define PG8_LDB(dst, b, h) do { _Pragma("unroll") for (int n = 0; n < 2; ++n) _Pragma("unroll") for (int k = 0; k < 2; ++k) dst[n][k] = *(const LAS bf16x8*)(lds + PG8_SB(b, h) + boff + n * 2048 + k * 1024); } while (0)
; #define PG8_MMA(ai, bj, At, Bt) do { __builtin_amdgcn_s_setprio(1); _Pragma("unroll") for (int m = 0; m < 4; ++m) _Pragma("unroll") for (int n = 0; n < 2; ++n) _Pragma("unroll") for (int k = 0; k < 2; ++k) \
;         acc[ai][bj][m][n] = __builtin_amdgcn_mfma_f32_16x16x32_bf16(Bt[n][k], At[m][k], acc[ai][bj][m][n], 0, 0, 0); __builtin_amdgcn_s_setprio(0); } while (0)
; #define PG8_WAIT_V(n) asm volatile("s_waitcnt vmcnt(" #n ")" ::: "memory")
; #define PG8_WAIT_L(n) asm volatile("s_waitcnt lgkmcnt(" #n ")" ::: "memory")
; #define PG8_BAR __builtin_amdgcn_s_barrier()
; #define PG8_SCHED __builtin_amdgcn_sched_barrier(0)
; template <class Epi, class Sched>
; __device__ __forceinline__ void gemm_phase(LAS unsigned char* lds, const int K, const Sched& S, const Epi& E) {
;     ...
;             PG8_WAIT_V(8); PG8_WAIT_L(0); PG8_BAR; PG8_MMA(1, 0, At, B0); PG8_MMA(1, 1, At, B1); PG8_BAR; PG8_SCHED;
;             PG8_LDB(B0, 1, 0); PG8_LDB(B1, 1, 1); PG8_SCHED; PG8_LDA(At, 1, 0); PG8_STAGE(PG8_SA(0, 1), a2 + hstep, voffA);
;             PG8_WAIT_V(8); PG8_WAIT_L(0); PG8_BAR; PG8_MMA(0, 0, At, B0); PG8_MMA(0, 1, At, B1); PG8_BAR; PG8_SCHED;
	v_mfma_f32_16x16x32_bf16 v[60:63], v[158:161], v[208:211], v[60:63]
	v_mfma_f32_16x16x32_bf16 v[56:59], v[184:187], v[208:211], v[56:59]
	v_mfma_f32_16x16x32_bf16 v[44:47], v[158:161], v[216:219], v[44:47]
	v_mfma_f32_16x16x32_bf16 v[40:43], v[184:187], v[216:219], v[40:43]
	v_mfma_f32_16x16x32_bf16 v[28:31], v[158:161], v[224:227], v[28:31]
	v_mfma_f32_16x16x32_bf16 v[24:27], v[184:187], v[224:227], v[24:27]
	v_mfma_f32_16x16x32_bf16 v[12:15], v[158:161], v[232:235], v[12:15]
	v_mfma_f32_16x16x32_bf16 v[8:11], v[184:187], v[232:235], v[8:11]
	s_setprio 0
	s_setprio 1
	v_mfma_f32_16x16x32_bf16 v[60:63], v[162:165], v[212:215], v[60:63]
	v_mfma_f32_16x16x32_bf16 v[56:59], v[188:191], v[212:215], v[56:59]
	v_mfma_f32_16x16x32_bf16 v[44:47], v[162:165], v[220:223], v[44:47]
	v_mfma_f32_16x16x32_bf16 v[40:43], v[188:191], v[220:223], v[40:43]
	v_mfma_f32_16x16x32_bf16 v[28:31], v[162:165], v[228:231], v[28:31]
	v_mfma_f32_16x16x32_bf16 v[24:27], v[188:191], v[228:231], v[24:27]
	v_mfma_f32_16x16x32_bf16 v[12:15], v[162:165], v[236:239], v[12:15]
	v_mfma_f32_16x16x32_bf16 v[8:11], v[188:191], v[236:239], v[8:11]
	s_setprio 0
	s_setprio 1
	v_mfma_f32_16x16x32_bf16 v[52:55], v[192:195], v[208:211], v[52:55]
	v_mfma_f32_16x16x32_bf16 v[48:51], v[200:203], v[208:211], v[48:51]
	v_mfma_f32_16x16x32_bf16 v[36:39], v[192:195], v[216:219], v[36:39]
	v_mfma_f32_16x16x32_bf16 v[32:35], v[200:203], v[216:219], v[32:35]
	v_mfma_f32_16x16x32_bf16 v[20:23], v[192:195], v[224:227], v[20:23]
	v_mfma_f32_16x16x32_bf16 v[16:19], v[200:203], v[224:227], v[16:19]
	v_mfma_f32_16x16x32_bf16 v[4:7], v[192:195], v[232:235], v[4:7]
	v_mfma_f32_16x16x32_bf16 v[0:3], v[200:203], v[232:235], v[0:3]
	s_setprio 0
	s_setprio 1
	v_mfma_f32_16x16x32_bf16 v[52:55], v[196:199], v[212:215], v[52:55]
	v_mfma_f32_16x16x32_bf16 v[48:51], v[204:207], v[212:215], v[48:51]
	v_mfma_f32_16x16x32_bf16 v[36:39], v[196:199], v[220:223], v[36:39]
	v_mfma_f32_16x16x32_bf16 v[32:35], v[204:207], v[220:223], v[32:35]
	v_mfma_f32_16x16x32_bf16 v[20:23], v[196:199], v[228:231], v[20:23]
	v_mfma_f32_16x16x32_bf16 v[16:19], v[204:207], v[228:231], v[16:19]
	v_mfma_f32_16x16x32_bf16 v[4:7], v[196:199], v[236:239], v[4:7]
	v_mfma_f32_16x16x32_bf16 v[0:3], v[204:207], v[236:239], v[0:3]
	s_barrier
	s_setprio 0
	s_add_i32 s16, 0, 0x18000
	v_add_u32_e32 v128, s16, v149
	s_add_i32 s17, 0, 0x1c000
	ds_read_b128 v[158:161], v128
	ds_read_b128 v[162:165], v128 offset:1024
	ds_read_b128 v[184:187], v128 offset:2048
	ds_read_b128 v[188:191], v128 offset:3072
	v_add_u32_e32 v128, s17, v149
	ds_read_b128 v[192:195], v128
	ds_read_b128 v[196:199], v128 offset:1024
	ds_read_b128 v[200:203], v128 offset:2048
	ds_read_b128 v[204:207], v128 offset:3072
	s_add_u32 s14, s54, 0x40000
	s_addc_u32 s15, s55, 0
	s_mov_b32 m0, s61
	v_lshl_add_u64 v[242:243], s[14:15], 0, v[138:139]
	ds_read_b128 v[208:211], v147 offset:32768
	ds_read_b128 v[212:215], v147 offset:33792
	ds_read_b128 v[216:219], v147 offset:34816
	ds_read_b128 v[220:223], v147 offset:35840
	ds_read_b128 v[224:227], v147 offset:36864
	ds_read_b128 v[228:231], v147 offset:37888
	ds_read_b128 v[232:235], v147 offset:38912
	ds_read_b128 v[236:239], v147 offset:39936
	global_load_lds_dwordx4 v[242:243], off
	v_lshl_add_u64 v[242:243], s[14:15], 0, v[142:143]
	s_mov_b32 m0, s62
	s_nop 0
	global_load_lds_dwordx4 v[242:243], off
	s_waitcnt vmcnt(8)
	s_waitcnt lgkmcnt(0)
	s_setprio 1
	s_barrier
	v_mfma_f32_16x16x32_bf16 v[124:127], v[158:161], v[208:211], v[124:127]
	v_mfma_f32_16x16x32_bf16 v[120:123], v[184:187], v[208:211], v[120:123]
	v_mfma_f32_16x16x32_bf16 v[108:111], v[158:161], v[216:219], v[108:111]
	v_mfma_f32_16x16x32_bf16 v[104:107], v[184:187], v[216:219], v[104:107]
	v_mfma_f32_16x16x32_bf16 v[92:95], v[158:161], v[224:227], v[92:95]
	v_mfma_f32_16x16x32_bf16 v[88:91], v[184:187], v[224:227], v[88:91]
	v_mfma_f32_16x16x32_bf16 v[76:79], v[158:161], v[232:235], v[76:79]
	v_mfma_f32_16x16x32_bf16 v[72:75], v[184:187], v[232:235], v[72:75]
	s_setprio 0
	s_setprio 1
	v_mfma_f32_16x16x32_bf16 v[124:127], v[162:165], v[212:215], v[124:127]
	v_mfma_f32_16x16x32_bf16 v[120:123], v[188:191], v[212:215], v[120:123]
	v_mfma_f32_16x16x32_bf16 v[108:111], v[162:165], v[220:223], v[108:111]
	v_mfma_f32_16x16x32_bf16 v[104:107], v[188:191], v[220:223], v[104:107]
	v_mfma_f32_16x16x32_bf16 v[92:95], v[162:165], v[228:231], v[92:95]
	v_mfma_f32_16x16x32_bf16 v[88:91], v[188:191], v[228:231], v[88:91]
	v_mfma_f32_16x16x32_bf16 v[76:79], v[162:165], v[236:239], v[76:79]
	v_mfma_f32_16x16x32_bf16 v[72:75], v[188:191], v[236:239], v[72:75]
	s_setprio 0
	s_setprio 1
	v_mfma_f32_16x16x32_bf16 v[116:119], v[192:195], v[208:211], v[116:119]
	v_mfma_f32_16x16x32_bf16 v[112:115], v[200:203], v[208:211], v[112:115]
	v_mfma_f32_16x16x32_bf16 v[100:103], v[192:195], v[216:219], v[100:103]
	v_mfma_f32_16x16x32_bf16 v[96:99], v[200:203], v[216:219], v[96:99]
	v_mfma_f32_16x16x32_bf16 v[84:87], v[192:195], v[224:227], v[84:87]
	v_mfma_f32_16x16x32_bf16 v[80:83], v[200:203], v[224:227], v[80:83]
	v_mfma_f32_16x16x32_bf16 v[68:71], v[192:195], v[232:235], v[68:71]
	v_mfma_f32_16x16x32_bf16 v[64:67], v[200:203], v[232:235], v[64:67]
	s_setprio 0
	s_setprio 1
	v_mfma_f32_16x16x32_bf16 v[116:119], v[196:199], v[212:215], v[116:119]
	v_mfma_f32_16x16x32_bf16 v[112:115], v[204:207], v[212:215], v[112:115]
	v_mfma_f32_16x16x32_bf16 v[100:103], v[196:199], v[220:223], v[100:103]
	v_mfma_f32_16x16x32_bf16 v[96:99], v[204:207], v[220:223], v[96:99]
	v_mfma_f32_16x16x32_bf16 v[84:87], v[196:199], v[228:231], v[84:87]
	v_mfma_f32_16x16x32_bf16 v[80:83], v[204:207], v[228:231], v[80:83]
	v_mfma_f32_16x16x32_bf16 v[68:71], v[196:199], v[236:239], v[68:71]
	v_mfma_f32_16x16x32_bf16 v[64:67], v[204:207], v[236:239], v[64:67]
	s_barrier
; #define PG8_STAGE(bufoff, gbase, voff) do { _Pragma("unroll") for (int _i = 0; _i < 2; ++_i) \
;         __builtin_amdgcn_global_load_lds((const unsigned*)((const char*)(gbase) + (voff)[_i]), (LAS unsigned*)(lds + (bufoff) + ldsw + _i * 8192), 16, 0, 0); } while (0)
; #define PG8_LDA(dst, b, h) do { _Pragma("unroll") for (int m = 0; m < 4; ++m) _Pragma("unroll") for (int k = 0; k < 2; ++k) dst[m][k] = *(const LAS bf16x8*)(lds + PG8_SA(b, h) + aoff + m * 2048 + k * 1024); } while (0)
; #define PG8_MMA(ai, bj, At, Bt) do { __builtin_amdgcn_s_setprio(1); _Pragma("unroll") for (int m = 0; m < 4; ++m) _Pragma("unroll") for (int n = 0; n < 2; ++n) _Pragma("unroll") for (int k = 0; k < 2; ++k) \
;         acc[ai][bj][m][n] = __builtin_amdgcn_mfma_f32_16x16x32_bf16(Bt[n][k], At[m][k], acc[ai][bj][m][n], 0, 0, 0); __builtin_amdgcn_s_setprio(0); } while (0)
; #define PG8_WAIT_V(n) asm volatile("s_waitcnt vmcnt(" #n ")" ::: "memory")
; #define PG8_WAIT_L(n) asm volatile("s_waitcnt lgkmcnt(" #n ")" ::: "memory")
; #define PG8_BAR __builtin_amdgcn_s_barrier()
; #define PG8_SCHED __builtin_amdgcn_sched_barrier(0)
; template <class Epi, class Sched>
; __device__ __forceinline__ void gemm_phase(LAS unsigned char* lds, const int K, const Sched& S, const Epi& E) {
;     ...
;             PG8_LDA(At, 1, 1); PG8_STAGE(PG8_SB(1, 0), b3, voffB); PG8_STAGE(PG8_SB(1, 1), b3 + hstep, voffB); PG8_STAGE(PG8_SA(1, 0), a3, voffA);
;             PG8_WAIT_V(8); PG8_WAIT_L(0); PG8_BAR; PG8_MMA(1, 0, At, B0); PG8_MMA(1, 1, At, B1); PG8_BAR; PG8_SCHED;
;         }
;         if (wr == 0) PG8_BAR;
	s_setprio 0
	s_add_i32 s14, s16, s58
	v_lshl_add_u64 v[166:167], v[166:167], 0, s[36:37]
	s_mov_b32 m0, s14
	ds_read_b128 v[208:211], v147 offset:49152
	ds_read_b128 v[212:215], v147 offset:50176
	ds_read_b128 v[216:219], v147 offset:51200
	ds_read_b128 v[220:223], v147 offset:52224
	ds_read_b128 v[224:227], v147 offset:53248
	ds_read_b128 v[228:231], v147 offset:54272
	ds_read_b128 v[232:235], v147 offset:55296
	ds_read_b128 v[236:239], v147 offset:56320
	global_load_lds_dwordx4 v[166:167], off
	s_add_i32 m0, s14, 0x2000
	s_add_u32 s14, s38, 0x40080
	v_lshl_add_u64 v[166:167], v[180:181], 0, s[36:37]
	s_addc_u32 s15, s39, 0
	s_add_i32 s16, s17, s58
	global_load_lds_dwordx4 v[166:167], off
	v_lshl_add_u64 v[166:167], s[14:15], 0, v[140:141]
	s_mov_b32 m0, s16
	s_nop 0
	global_load_lds_dwordx4 v[166:167], off
	v_lshl_add_u64 v[166:167], s[14:15], 0, v[144:145]
	s_add_i32 m0, s16, 0x2000
	s_nop 0
	global_load_lds_dwordx4 v[166:167], off
	v_lshl_add_u64 v[166:167], v[182:183], 0, s[36:37]
	s_mov_b32 m0, s64
	s_nop 0
	global_load_lds_dwordx4 v[166:167], off
	v_lshl_add_u64 v[166:167], v[240:241], 0, s[36:37]
	s_mov_b32 m0, s65
	s_nop 0
	global_load_lds_dwordx4 v[166:167], off
	s_waitcnt vmcnt(8)
	s_waitcnt lgkmcnt(0)
	s_setprio 1
	s_barrier
	v_mfma_f32_16x16x32_bf16 v[60:63], v[158:161], v[208:211], v[60:63]
	v_mfma_f32_16x16x32_bf16 v[56:59], v[184:187], v[208:211], v[56:59]
	v_mfma_f32_16x16x32_bf16 v[44:47], v[158:161], v[216:219], v[44:47]
	v_mfma_f32_16x16x32_bf16 v[40:43], v[184:187], v[216:219], v[40:43]
	v_mfma_f32_16x16x32_bf16 v[28:31], v[158:161], v[224:227], v[28:31]
	v_mfma_f32_16x16x32_bf16 v[24:27], v[184:187], v[224:227], v[24:27]
	v_mfma_f32_16x16x32_bf16 v[12:15], v[158:161], v[232:235], v[12:15]
	v_mfma_f32_16x16x32_bf16 v[8:11], v[184:187], v[232:235], v[8:11]
	s_setprio 0
	s_setprio 1
	v_mfma_f32_16x16x32_bf16 v[60:63], v[162:165], v[212:215], v[60:63]
	v_mfma_f32_16x16x32_bf16 v[56:59], v[188:191], v[212:215], v[56:59]
	v_mfma_f32_16x16x32_bf16 v[44:47], v[162:165], v[220:223], v[44:47]
	v_mfma_f32_16x16x32_bf16 v[40:43], v[188:191], v[220:223], v[40:43]
	v_mfma_f32_16x16x32_bf16 v[28:31], v[162:165], v[228:231], v[28:31]
	v_mfma_f32_16x16x32_bf16 v[24:27], v[188:191], v[228:231], v[24:27]
	v_mfma_f32_16x16x32_bf16 v[12:15], v[162:165], v[236:239], v[12:15]
	v_mfma_f32_16x16x32_bf16 v[8:11], v[188:191], v[236:239], v[8:11]
	s_setprio 0
	s_setprio 1
	v_mfma_f32_16x16x32_bf16 v[52:55], v[192:195], v[208:211], v[52:55]
	v_mfma_f32_16x16x32_bf16 v[48:51], v[200:203], v[208:211], v[48:51]
	v_mfma_f32_16x16x32_bf16 v[36:39], v[192:195], v[216:219], v[36:39]
	v_mfma_f32_16x16x32_bf16 v[32:35], v[200:203], v[216:219], v[32:35]
	v_mfma_f32_16x16x32_bf16 v[20:23], v[192:195], v[224:227], v[20:23]
	v_mfma_f32_16x16x32_bf16 v[16:19], v[200:203], v[224:227], v[16:19]
	v_mfma_f32_16x16x32_bf16 v[4:7], v[192:195], v[232:235], v[4:7]
	v_mfma_f32_16x16x32_bf16 v[0:3], v[200:203], v[232:235], v[0:3]
	s_setprio 0
	s_setprio 1
	v_mfma_f32_16x16x32_bf16 v[52:55], v[196:199], v[212:215], v[52:55]
	v_mfma_f32_16x16x32_bf16 v[48:51], v[204:207], v[212:215], v[48:51]
	v_mfma_f32_16x16x32_bf16 v[36:39], v[196:199], v[220:223], v[36:39]
	v_mfma_f32_16x16x32_bf16 v[32:35], v[204:207], v[220:223], v[32:35]
	v_mfma_f32_16x16x32_bf16 v[20:23], v[196:199], v[228:231], v[20:23]
	v_mfma_f32_16x16x32_bf16 v[16:19], v[204:207], v[228:231], v[16:19]
	v_mfma_f32_16x16x32_bf16 v[4:7], v[196:199], v[236:239], v[4:7]
	v_mfma_f32_16x16x32_bf16 v[0:3], v[204:207], v[236:239], v[0:3]
	s_barrier
	s_setprio 0
	s_add_i32 s13, s13, 2
	s_add_u32 s8, s8, 0x100
	s_addc_u32 s9, s9, 0
	s_add_u32 s11, s11, 0x100
	s_addc_u32 s12, s12, 0
	s_cmp_gt_u32 s13, 13
	s_cbranch_scc0 .LBB0_403
	s_and_b64 vcc, exec, s[42:43]
	s_cbranch_vccz .LBB0_406
	s_barrier

; #define PG8_STAGE(bufoff, gbase, voff) do { _Pragma("unroll") for (int _i = 0; _i < 2; ++_i) \
;         __builtin_amdgcn_global_load_lds((const unsigned*)((const char*)(gbase) + (voff)[_i]), (LAS unsigned*)(lds + (bufoff) + ldsw + _i * 8192), 16, 0, 0); } while (0)
; #define PG8_LDA(dst, b, h) do { _Pragma("unroll") for (int m = 0; m < 4; ++m) _Pragma("unroll") for (int k = 0; k < 2; ++k) dst[m][k] = *(const LAS bf16x8*)(lds + PG8_SA(b, h) + aoff + m * 2048 + k * 1024); } while (0)
; #define PG8_LDB(dst, b, h) do { _Pragma("unroll") for (int n = 0; n < 2; ++n) _Pragma("unroll") for (int k = 0; k < 2; ++k) dst[n][k] = *(const LAS bf16x8*)(lds + PG8_SB(b, h) + boff + n * 2048 + k * 1024); } while (0)
; #define PG8_MMA(ai, bj, At, Bt) do { __builtin_amdgcn_s_setprio(1); _Pragma("unroll") for (int m = 0; m < 4; ++m) _Pragma("unroll") for (int n = 0; n < 2; ++n) _Pragma("unroll") for (int k = 0; k < 2; ++k) \
;         acc[ai][bj][m][n] = __builtin_amdgcn_mfma_f32_16x16x32_bf16(Bt[n][k], At[m][k], acc[ai][bj][m][n], 0, 0, 0); __builtin_amdgcn_s_setprio(0); } while (0)
; #define PG8_WAIT_V(n) asm volatile("s_waitcnt vmcnt(" #n ")" ::: "memory")
; #define PG8_WAIT_L(n) asm volatile("s_waitcnt lgkmcnt(" #n ")" ::: "memory")
; #define PG8_BAR __builtin_amdgcn_s_barrier()
; #define PG8_SCHED __builtin_amdgcn_sched_barrier(0)
; template <class Epi, class Sched>
; __device__ __forceinline__ void gemm_phase(LAS unsigned char* lds, const int K, const Sched& S, const Epi& E) {
;     ...
;         for (int t = 0; t < nt; t += 2) {
;             const bool last = (t == nt - 2);
;             const char* a1 = cA + (size_t)(t + 1) * kstep;
;             const char* a2 = last ? nA : cA + (size_t)(t + 2) * kstep; const char* b2 = last ? nB : cB + (size_t)(t + 2) * kstep;
;             const char* a3 = a2 + kstep; const char* b3 = b2 + kstep;
;             PG8_LDB(B0, 0, 0); PG8_LDB(B1, 0, 1); PG8_SCHED; PG8_LDA(At, 0, 0); PG8_STAGE(PG8_SA(1, 1), a1 + hstep, voffA);
;             PG8_WAIT_V(8); PG8_WAIT_L(0); PG8_BAR; PG8_MMA(0, 0, At, B0); PG8_MMA(0, 1, At, B1); PG8_BAR; PG8_SCHED;
;             PG8_LDA(At, 0, 1); PG8_STAGE(PG8_SB(0, 0), b2, voffB); PG8_STAGE(PG8_SB(0, 1), b2 + hstep, voffB); PG8_STAGE(PG8_SA(0, 0), a2, voffA);
;             PG8_WAIT_V(8); PG8_WAIT_L(0); PG8_BAR; PG8_MMA(1, 0, At, B0); PG8_MMA(1, 1, At, B1); PG8_BAR; PG8_SCHED;
.LBB0_511:
	s_add_i32 s14, s8, 0xfaf9e080
	s_cmp_lg_u32 s13, 60
	s_cselect_b32 s14, s14, 0
	s_add_u32 s40, s28, s14
	s_addc_u32 s41, s29, 0
	s_add_i32 s15, 0, 0x10000
	s_add_u32 s38, s34, s14
	s_addc_u32 s39, s35, 0
	s_add_i32 s16, 0, 0x14000
	v_add_u32_e32 v164, s15, v145
	v_add_u32_e32 v180, s16, v145
	ds_read_b128 v[152:155], v164
	ds_read_b128 v[156:159], v164 offset:1024
	ds_read_b128 v[160:163], v164 offset:2048
	ds_read_b128 v[164:167], v164 offset:3072
	ds_read_b128 v[184:187], v180
	ds_read_b128 v[188:191], v180 offset:1024
	ds_read_b128 v[192:195], v180 offset:2048
	ds_read_b128 v[196:199], v180 offset:3072
	v_lshl_add_u64 v[180:181], v[146:147], 0, s[8:9]
	s_add_i32 m0, s2, 0xc000
	ds_read_b128 v[200:203], v151
	ds_read_b128 v[204:207], v151 offset:1024
	ds_read_b128 v[208:211], v151 offset:2048
	ds_read_b128 v[212:215], v151 offset:3072
	ds_read_b128 v[216:219], v151 offset:4096
	ds_read_b128 v[220:223], v151 offset:5120
	ds_read_b128 v[224:227], v151 offset:6144
	ds_read_b128 v[228:231], v151 offset:7168
	global_load_lds_dwordx4 v[180:181], off
	v_lshl_add_u64 v[180:181], v[148:149], 0, s[8:9]
	s_add_i32 m0, s2, 0xe000
	s_nop 0
	global_load_lds_dwordx4 v[180:181], off
	s_waitcnt vmcnt(8)
	s_waitcnt lgkmcnt(0)
	s_setprio 1
	s_barrier
	v_mfma_f32_16x16x32_bf16 v[124:127], v[152:155], v[200:203], v[124:127]
	v_mfma_f32_16x16x32_bf16 v[120:123], v[160:163], v[200:203], v[120:123]
	v_mfma_f32_16x16x32_bf16 v[108:111], v[152:155], v[208:211], v[108:111]
	v_mfma_f32_16x16x32_bf16 v[104:107], v[160:163], v[208:211], v[104:107]
	v_mfma_f32_16x16x32_bf16 v[92:95], v[152:155], v[216:219], v[92:95]
	v_mfma_f32_16x16x32_bf16 v[88:91], v[160:163], v[216:219], v[88:91]
	v_mfma_f32_16x16x32_bf16 v[76:79], v[152:155], v[224:227], v[76:79]
	v_mfma_f32_16x16x32_bf16 v[72:75], v[160:163], v[224:227], v[72:75]
	s_setprio 0
	s_setprio 1
	v_mfma_f32_16x16x32_bf16 v[124:127], v[156:159], v[204:207], v[124:127]
	v_mfma_f32_16x16x32_bf16 v[120:123], v[164:167], v[204:207], v[120:123]
	v_mfma_f32_16x16x32_bf16 v[108:111], v[156:159], v[212:215], v[108:111]
	v_mfma_f32_16x16x32_bf16 v[104:107], v[164:167], v[212:215], v[104:107]
	v_mfma_f32_16x16x32_bf16 v[92:95], v[156:159], v[220:223], v[92:95]
	v_mfma_f32_16x16x32_bf16 v[88:91], v[164:167], v[220:223], v[88:91]
	v_mfma_f32_16x16x32_bf16 v[76:79], v[156:159], v[228:231], v[76:79]
	v_mfma_f32_16x16x32_bf16 v[72:75], v[164:167], v[228:231], v[72:75]
	s_setprio 0
	s_setprio 1
	v_mfma_f32_16x16x32_bf16 v[116:119], v[184:187], v[200:203], v[116:119]
	v_mfma_f32_16x16x32_bf16 v[112:115], v[192:195], v[200:203], v[112:115]
	v_mfma_f32_16x16x32_bf16 v[100:103], v[184:187], v[208:211], v[100:103]
	v_mfma_f32_16x16x32_bf16 v[96:99], v[192:195], v[208:211], v[96:99]
	v_mfma_f32_16x16x32_bf16 v[84:87], v[184:187], v[216:219], v[84:87]
	v_mfma_f32_16x16x32_bf16 v[80:83], v[192:195], v[216:219], v[80:83]
	v_mfma_f32_16x16x32_bf16 v[68:71], v[184:187], v[224:227], v[68:71]
	v_mfma_f32_16x16x32_bf16 v[64:67], v[192:195], v[224:227], v[64:67]
	s_setprio 0
	s_setprio 1
	v_mfma_f32_16x16x32_bf16 v[116:119], v[188:191], v[204:207], v[116:119]
	v_mfma_f32_16x16x32_bf16 v[112:115], v[196:199], v[204:207], v[112:115]
	v_mfma_f32_16x16x32_bf16 v[100:103], v[188:191], v[212:215], v[100:103]
	v_mfma_f32_16x16x32_bf16 v[96:99], v[196:199], v[212:215], v[96:99]
	v_mfma_f32_16x16x32_bf16 v[84:87], v[188:191], v[220:223], v[84:87]
	v_mfma_f32_16x16x32_bf16 v[80:83], v[196:199], v[220:223], v[80:83]
	v_mfma_f32_16x16x32_bf16 v[68:71], v[188:191], v[228:231], v[68:71]
	v_mfma_f32_16x16x32_bf16 v[64:67], v[196:199], v[228:231], v[64:67]
	s_barrier
	s_setprio 0
	s_add_i32 s14, s15, s1
	v_lshl_add_u64 v[180:181], s[38:39], 0, v[128:129]
	s_mov_b32 m0, s14
	ds_read_b128 v[200:203], v151 offset:16384
	ds_read_b128 v[204:207], v151 offset:17408
	ds_read_b128 v[208:211], v151 offset:18432
	ds_read_b128 v[212:215], v151 offset:19456
	ds_read_b128 v[216:219], v151 offset:20480
	ds_read_b128 v[220:223], v151 offset:21504
	ds_read_b128 v[224:227], v151 offset:22528
	ds_read_b128 v[228:231], v151 offset:23552
	global_load_lds_dwordx4 v[180:181], off
	s_add_i32 m0, s14, 0x2000
	s_add_u32 s14, s38, 0x100000
	v_lshl_add_u64 v[182:183], s[38:39], 0, v[138:139]
	s_addc_u32 s15, s39, 0
	s_add_i32 s16, s16, s1
	global_load_lds_dwordx4 v[182:183], off
	v_lshl_add_u64 v[232:233], s[14:15], 0, v[128:129]
	s_mov_b32 m0, s16
	v_lshl_add_u64 v[234:235], s[40:41], 0, v[140:141]
	global_load_lds_dwordx4 v[232:233], off
	v_lshl_add_u64 v[232:233], s[14:15], 0, v[138:139]
	s_add_i32 m0, s16, 0x2000
	s_nop 0
	global_load_lds_dwordx4 v[232:233], off
	v_lshl_add_u64 v[232:233], s[40:41], 0, v[142:143]
	s_mov_b32 m0, s2
	s_nop 0
	global_load_lds_dwordx4 v[232:233], off
	s_mov_b32 m0, s3
	s_nop 0
	global_load_lds_dwordx4 v[234:235], off
	s_waitcnt vmcnt(8)
	s_waitcnt lgkmcnt(0)
	s_setprio 1
	s_barrier
; #define PG8_STAGE(bufoff, gbase, voff) do { _Pragma("unroll") for (int _i = 0; _i < 2; ++_i) \
;         __builtin_amdgcn_global_load_lds((const unsigned*)((const char*)(gbase) + (voff)[_i]), (LAS unsigned*)(lds + (bufoff) + ldsw + _i * 8192), 16, 0, 0); } while (0)
; #define PG8_LDA(dst, b, h) do { _Pragma("unroll") for (int m = 0; m < 4; ++m) _Pragma("unroll") for (int k = 0; k < 2; ++k) dst[m][k] = *(const LAS bf16x8*)(lds + PG8_SA(b, h) + aoff + m * 2048 + k * 1024); } while (0)
; #define PG8_LDB(dst, b, h) do { _Pragma("unroll") for (int n = 0; n < 2; ++n) _Pragma("unroll") for (int k = 0; k < 2; ++k) dst[n][k] = *(const LAS bf16x8*)(lds + PG8_SB(b, h) + boff + n * 2048 + k * 1024); } while (0)
; #define PG8_MMA(ai, bj, At, Bt) do { __builtin_amdgcn_s_setprio(1); _Pragma("unroll") for (int m = 0; m < 4; ++m) _Pragma("unroll") for (int n = 0; n < 2; ++n) _Pragma("unroll") for (int k = 0; k < 2; ++k) \
;         acc[ai][bj][m][n] = __builtin_amdgcn_mfma_f32_16x16x32_bf16(Bt[n][k], At[m][k], acc[ai][bj][m][n], 0, 0, 0); __builtin_amdgcn_s_setprio(0); } while (0)
; #define PG8_WAIT_V(n) asm volatile("s_waitcnt vmcnt(" #n ")" ::: "memory")
; #define PG8_WAIT_L(n) asm volatile("s_waitcnt lgkmcnt(" #n ")" ::: "memory")
; #define PG8_BAR __builtin_amdgcn_s_barrier()
; #define PG8_SCHED __builtin_amdgcn_sched_barrier(0)
; template <class Epi, class Sched>
; __device__ __forceinline__ void gemm_phase(LAS unsigned char* lds, const int K, const Sched& S, const Epi& E) {
;     ...
;             PG8_WAIT_V(8); PG8_WAIT_L(0); PG8_BAR; PG8_MMA(1, 0, At, B0); PG8_MMA(1, 1, At, B1); PG8_BAR; PG8_SCHED;
;             PG8_LDB(B0, 1, 0); PG8_LDB(B1, 1, 1); PG8_SCHED; PG8_LDA(At, 1, 0); PG8_STAGE(PG8_SA(0, 1), a2 + hstep, voffA);
;             PG8_WAIT_V(8); PG8_WAIT_L(0); PG8_BAR; PG8_MMA(0, 0, At, B0); PG8_MMA(0, 1, At, B1); PG8_BAR; PG8_SCHED;
	v_mfma_f32_16x16x32_bf16 v[60:63], v[152:155], v[200:203], v[60:63]
	v_mfma_f32_16x16x32_bf16 v[56:59], v[160:163], v[200:203], v[56:59]
	v_mfma_f32_16x16x32_bf16 v[44:47], v[152:155], v[208:211], v[44:47]
	v_mfma_f32_16x16x32_bf16 v[40:43], v[160:163], v[208:211], v[40:43]
	v_mfma_f32_16x16x32_bf16 v[28:31], v[152:155], v[216:219], v[28:31]
	v_mfma_f32_16x16x32_bf16 v[24:27], v[160:163], v[216:219], v[24:27]
	v_mfma_f32_16x16x32_bf16 v[12:15], v[152:155], v[224:227], v[12:15]
	v_mfma_f32_16x16x32_bf16 v[8:11], v[160:163], v[224:227], v[8:11]
	s_setprio 0
	s_setprio 1
	v_mfma_f32_16x16x32_bf16 v[60:63], v[156:159], v[204:207], v[60:63]
	v_mfma_f32_16x16x32_bf16 v[56:59], v[164:167], v[204:207], v[56:59]
	v_mfma_f32_16x16x32_bf16 v[44:47], v[156:159], v[212:215], v[44:47]
	v_mfma_f32_16x16x32_bf16 v[40:43], v[164:167], v[212:215], v[40:43]
	v_mfma_f32_16x16x32_bf16 v[28:31], v[156:159], v[220:223], v[28:31]
	v_mfma_f32_16x16x32_bf16 v[24:27], v[164:167], v[220:223], v[24:27]
	v_mfma_f32_16x16x32_bf16 v[12:15], v[156:159], v[228:231], v[12:15]
	v_mfma_f32_16x16x32_bf16 v[8:11], v[164:167], v[228:231], v[8:11]
	s_setprio 0
	s_setprio 1
	v_mfma_f32_16x16x32_bf16 v[52:55], v[184:187], v[200:203], v[52:55]
	v_mfma_f32_16x16x32_bf16 v[48:51], v[192:195], v[200:203], v[48:51]
	v_mfma_f32_16x16x32_bf16 v[36:39], v[184:187], v[208:211], v[36:39]
	v_mfma_f32_16x16x32_bf16 v[32:35], v[192:195], v[208:211], v[32:35]
	v_mfma_f32_16x16x32_bf16 v[20:23], v[184:187], v[216:219], v[20:23]
	v_mfma_f32_16x16x32_bf16 v[16:19], v[192:195], v[216:219], v[16:19]
	v_mfma_f32_16x16x32_bf16 v[4:7], v[184:187], v[224:227], v[4:7]
	v_mfma_f32_16x16x32_bf16 v[0:3], v[192:195], v[224:227], v[0:3]
	s_setprio 0
	s_setprio 1
	v_mfma_f32_16x16x32_bf16 v[52:55], v[188:191], v[204:207], v[52:55]
	v_mfma_f32_16x16x32_bf16 v[48:51], v[196:199], v[204:207], v[48:51]
	v_mfma_f32_16x16x32_bf16 v[36:39], v[188:191], v[212:215], v[36:39]
	v_mfma_f32_16x16x32_bf16 v[32:35], v[196:199], v[212:215], v[32:35]
	v_mfma_f32_16x16x32_bf16 v[20:23], v[188:191], v[220:223], v[20:23]
	v_mfma_f32_16x16x32_bf16 v[16:19], v[196:199], v[220:223], v[16:19]
	v_mfma_f32_16x16x32_bf16 v[4:7], v[188:191], v[228:231], v[4:7]
	v_mfma_f32_16x16x32_bf16 v[0:3], v[196:199], v[228:231], v[0:3]
	s_barrier
	s_setprio 0
	s_add_i32 s16, 0, 0x18000
	s_add_i32 s17, 0, 0x1c000
	v_add_u32_e32 v164, s16, v145
	v_add_u32_e32 v196, s17, v145
	ds_read_b128 v[152:155], v164
	ds_read_b128 v[156:159], v164 offset:1024
	ds_read_b128 v[160:163], v164 offset:2048
	ds_read_b128 v[164:167], v164 offset:3072
	ds_read_b128 v[184:187], v196
	ds_read_b128 v[188:191], v196 offset:1024
	ds_read_b128 v[192:195], v196 offset:2048
	ds_read_b128 v[196:199], v196 offset:3072
	s_add_u32 s14, s40, 0x100000
	s_addc_u32 s15, s41, 0
	s_mov_b32 m0, s4
	v_lshl_add_u64 v[236:237], s[14:15], 0, v[142:143]
	ds_read_b128 v[200:203], v151 offset:32768
	ds_read_b128 v[204:207], v151 offset:33792
	ds_read_b128 v[208:211], v151 offset:34816
	ds_read_b128 v[212:215], v151 offset:35840
	ds_read_b128 v[216:219], v151 offset:36864
	ds_read_b128 v[220:223], v151 offset:37888
	ds_read_b128 v[224:227], v151 offset:38912
	ds_read_b128 v[228:231], v151 offset:39936
	global_load_lds_dwordx4 v[236:237], off
	v_lshl_add_u64 v[236:237], s[14:15], 0, v[140:141]
	s_mov_b32 m0, s5
	s_nop 0
	global_load_lds_dwordx4 v[236:237], off
	s_waitcnt vmcnt(8)
	s_waitcnt lgkmcnt(0)
	s_setprio 1
	s_barrier
	v_mfma_f32_16x16x32_bf16 v[124:127], v[152:155], v[200:203], v[124:127]
	v_mfma_f32_16x16x32_bf16 v[120:123], v[160:163], v[200:203], v[120:123]
	v_mfma_f32_16x16x32_bf16 v[108:111], v[152:155], v[208:211], v[108:111]
	v_mfma_f32_16x16x32_bf16 v[104:107], v[160:163], v[208:211], v[104:107]
	v_mfma_f32_16x16x32_bf16 v[92:95], v[152:155], v[216:219], v[92:95]
	v_mfma_f32_16x16x32_bf16 v[88:91], v[160:163], v[216:219], v[88:91]
	v_mfma_f32_16x16x32_bf16 v[76:79], v[152:155], v[224:227], v[76:79]
	v_mfma_f32_16x16x32_bf16 v[72:75], v[160:163], v[224:227], v[72:75]
	s_setprio 0
	s_setprio 1
	v_mfma_f32_16x16x32_bf16 v[124:127], v[156:159], v[204:207], v[124:127]
	v_mfma_f32_16x16x32_bf16 v[120:123], v[164:167], v[204:207], v[120:123]
	v_mfma_f32_16x16x32_bf16 v[108:111], v[156:159], v[212:215], v[108:111]
	v_mfma_f32_16x16x32_bf16 v[104:107], v[164:167], v[212:215], v[104:107]
	v_mfma_f32_16x16x32_bf16 v[92:95], v[156:159], v[220:223], v[92:95]
	v_mfma_f32_16x16x32_bf16 v[88:91], v[164:167], v[220:223], v[88:91]
	v_mfma_f32_16x16x32_bf16 v[76:79], v[156:159], v[228:231], v[76:79]
	v_mfma_f32_16x16x32_bf16 v[72:75], v[164:167], v[228:231], v[72:75]
	s_setprio 0
	s_setprio 1
	v_mfma_f32_16x16x32_bf16 v[116:119], v[184:187], v[200:203], v[116:119]
	v_mfma_f32_16x16x32_bf16 v[112:115], v[192:195], v[200:203], v[112:115]
	v_mfma_f32_16x16x32_bf16 v[100:103], v[184:187], v[208:211], v[100:103]
	v_mfma_f32_16x16x32_bf16 v[96:99], v[192:195], v[208:211], v[96:99]
	v_mfma_f32_16x16x32_bf16 v[84:87], v[184:187], v[216:219], v[84:87]
	v_mfma_f32_16x16x32_bf16 v[80:83], v[192:195], v[216:219], v[80:83]
	v_mfma_f32_16x16x32_bf16 v[68:71], v[184:187], v[224:227], v[68:71]
	v_mfma_f32_16x16x32_bf16 v[64:67], v[192:195], v[224:227], v[64:67]
	s_setprio 0
	s_setprio 1
	v_mfma_f32_16x16x32_bf16 v[116:119], v[188:191], v[204:207], v[116:119]
	v_mfma_f32_16x16x32_bf16 v[112:115], v[196:199], v[204:207], v[112:115]
	v_mfma_f32_16x16x32_bf16 v[100:103], v[188:191], v[212:215], v[100:103]
	v_mfma_f32_16x16x32_bf16 v[96:99], v[196:199], v[212:215], v[96:99]
	v_mfma_f32_16x16x32_bf16 v[84:87], v[188:191], v[220:223], v[84:87]
	v_mfma_f32_16x16x32_bf16 v[80:83], v[196:199], v[220:223], v[80:83]
	v_mfma_f32_16x16x32_bf16 v[68:71], v[188:191], v[228:231], v[68:71]
	v_mfma_f32_16x16x32_bf16 v[64:67], v[196:199], v[228:231], v[64:67]
	s_barrier
; #define PG8_STAGE(bufoff, gbase, voff) do { _Pragma("unroll") for (int _i = 0; _i < 2; ++_i) \
;         __builtin_amdgcn_global_load_lds((const unsigned*)((const char*)(gbase) + (voff)[_i]), (LAS unsigned*)(lds + (bufoff) + ldsw + _i * 8192), 16, 0, 0); } while (0)
; #define PG8_LDA(dst, b, h) do { _Pragma("unroll") for (int m = 0; m < 4; ++m) _Pragma("unroll") for (int k = 0; k < 2; ++k) dst[m][k] = *(const LAS bf16x8*)(lds + PG8_SA(b, h) + aoff + m * 2048 + k * 1024); } while (0)
; #define PG8_MMA(ai, bj, At, Bt) do { __builtin_amdgcn_s_setprio(1); _Pragma("unroll") for (int m = 0; m < 4; ++m) _Pragma("unroll") for (int n = 0; n < 2; ++n) _Pragma("unroll") for (int k = 0; k < 2; ++k) \
;         acc[ai][bj][m][n] = __builtin_amdgcn_mfma_f32_16x16x32_bf16(Bt[n][k], At[m][k], acc[ai][bj][m][n], 0, 0, 0); __builtin_amdgcn_s_setprio(0); } while (0)
; #define PG8_WAIT_V(n) asm volatile("s_waitcnt vmcnt(" #n ")" ::: "memory")
; #define PG8_WAIT_L(n) asm volatile("s_waitcnt lgkmcnt(" #n ")" ::: "memory")
; #define PG8_BAR __builtin_amdgcn_s_barrier()
; #define PG8_SCHED __builtin_amdgcn_sched_barrier(0)
; template <class Epi, class Sched>
; __device__ __forceinline__ void gemm_phase(LAS unsigned char* lds, const int K, const Sched& S, const Epi& E) {
;     ...
;             PG8_LDA(At, 1, 1); PG8_STAGE(PG8_SB(1, 0), b3, voffB); PG8_STAGE(PG8_SB(1, 1), b3 + hstep, voffB); PG8_STAGE(PG8_SA(1, 0), a3, voffA);
;             PG8_WAIT_V(8); PG8_WAIT_L(0); PG8_BAR; PG8_MMA(1, 0, At, B0); PG8_MMA(1, 1, At, B1); PG8_BAR; PG8_SCHED;
;         }
;         if (wr == 0) PG8_BAR;
	s_setprio 0
	s_add_i32 s14, s16, s1
	v_lshl_add_u64 v[180:181], v[180:181], 0, s[36:37]
	s_mov_b32 m0, s14
	ds_read_b128 v[200:203], v151 offset:49152
	ds_read_b128 v[204:207], v151 offset:50176
	ds_read_b128 v[208:211], v151 offset:51200
	ds_read_b128 v[212:215], v151 offset:52224
	ds_read_b128 v[216:219], v151 offset:53248
	ds_read_b128 v[220:223], v151 offset:54272
	ds_read_b128 v[224:227], v151 offset:55296
	ds_read_b128 v[228:231], v151 offset:56320
	global_load_lds_dwordx4 v[180:181], off
	s_add_i32 m0, s14, 0x2000
	s_add_u32 s14, s38, 0x100080
	v_lshl_add_u64 v[180:181], v[182:183], 0, s[36:37]
	s_addc_u32 s15, s39, 0
	s_add_i32 s16, s17, s1
	global_load_lds_dwordx4 v[180:181], off
	v_lshl_add_u64 v[180:181], s[14:15], 0, v[128:129]
	s_mov_b32 m0, s16
	s_nop 0
	global_load_lds_dwordx4 v[180:181], off
	v_lshl_add_u64 v[180:181], s[14:15], 0, v[138:139]
	s_add_i32 m0, s16, 0x2000
	s_nop 0
	global_load_lds_dwordx4 v[180:181], off
	v_lshl_add_u64 v[180:181], v[232:233], 0, s[36:37]
	s_mov_b32 m0, s11
	s_nop 0
	global_load_lds_dwordx4 v[180:181], off
	v_lshl_add_u64 v[180:181], v[234:235], 0, s[36:37]
	s_mov_b32 m0, s12
	s_nop 0
	global_load_lds_dwordx4 v[180:181], off
	s_waitcnt vmcnt(8)
	s_waitcnt lgkmcnt(0)
	s_setprio 1
	s_barrier
	v_mfma_f32_16x16x32_bf16 v[60:63], v[152:155], v[200:203], v[60:63]
	v_mfma_f32_16x16x32_bf16 v[56:59], v[160:163], v[200:203], v[56:59]
	v_mfma_f32_16x16x32_bf16 v[44:47], v[152:155], v[208:211], v[44:47]
	v_mfma_f32_16x16x32_bf16 v[40:43], v[160:163], v[208:211], v[40:43]
	v_mfma_f32_16x16x32_bf16 v[28:31], v[152:155], v[216:219], v[28:31]
	v_mfma_f32_16x16x32_bf16 v[24:27], v[160:163], v[216:219], v[24:27]
	v_mfma_f32_16x16x32_bf16 v[12:15], v[152:155], v[224:227], v[12:15]
	v_mfma_f32_16x16x32_bf16 v[8:11], v[160:163], v[224:227], v[8:11]
	s_setprio 0
	s_setprio 1
	v_mfma_f32_16x16x32_bf16 v[60:63], v[156:159], v[204:207], v[60:63]
	v_mfma_f32_16x16x32_bf16 v[56:59], v[164:167], v[204:207], v[56:59]
	v_mfma_f32_16x16x32_bf16 v[44:47], v[156:159], v[212:215], v[44:47]
	v_mfma_f32_16x16x32_bf16 v[40:43], v[164:167], v[212:215], v[40:43]
	v_mfma_f32_16x16x32_bf16 v[28:31], v[156:159], v[220:223], v[28:31]
	v_mfma_f32_16x16x32_bf16 v[24:27], v[164:167], v[220:223], v[24:27]
	v_mfma_f32_16x16x32_bf16 v[12:15], v[156:159], v[228:231], v[12:15]
	v_mfma_f32_16x16x32_bf16 v[8:11], v[164:167], v[228:231], v[8:11]
	s_setprio 0
	s_setprio 1
	v_mfma_f32_16x16x32_bf16 v[52:55], v[184:187], v[200:203], v[52:55]
	v_mfma_f32_16x16x32_bf16 v[48:51], v[192:195], v[200:203], v[48:51]
	v_mfma_f32_16x16x32_bf16 v[36:39], v[184:187], v[208:211], v[36:39]
	v_mfma_f32_16x16x32_bf16 v[32:35], v[192:195], v[208:211], v[32:35]
	v_mfma_f32_16x16x32_bf16 v[20:23], v[184:187], v[216:219], v[20:23]
	v_mfma_f32_16x16x32_bf16 v[16:19], v[192:195], v[216:219], v[16:19]
	v_mfma_f32_16x16x32_bf16 v[4:7], v[184:187], v[224:227], v[4:7]
	v_mfma_f32_16x16x32_bf16 v[0:3], v[192:195], v[224:227], v[0:3]
	s_setprio 0
	s_setprio 1
	v_mfma_f32_16x16x32_bf16 v[52:55], v[188:191], v[204:207], v[52:55]
	v_mfma_f32_16x16x32_bf16 v[48:51], v[196:199], v[204:207], v[48:51]
	v_mfma_f32_16x16x32_bf16 v[36:39], v[188:191], v[212:215], v[36:39]
	v_mfma_f32_16x16x32_bf16 v[32:35], v[196:199], v[212:215], v[32:35]
	v_mfma_f32_16x16x32_bf16 v[20:23], v[188:191], v[220:223], v[20:23]
	v_mfma_f32_16x16x32_bf16 v[16:19], v[196:199], v[220:223], v[16:19]
	v_mfma_f32_16x16x32_bf16 v[4:7], v[188:191], v[228:231], v[4:7]
	v_mfma_f32_16x16x32_bf16 v[0:3], v[196:199], v[228:231], v[0:3]
	s_barrier
	s_setprio 0
	s_add_i32 s13, s13, 2
	s_add_u32 s8, s8, 0x100
	s_addc_u32 s9, s9, 0
	s_cmp_gt_u32 s13, 61
	s_cbranch_scc0 .LBB0_511
	s_cmpk_lt_u32 s0, 0x100
	s_cbranch_scc0 .LBB0_514
	s_barrier

; #define PG8_STAGE(bufoff, gbase, voff) do { _Pragma("unroll") for (int _i = 0; _i < 2; ++_i) \
;         __builtin_amdgcn_global_load_lds((const unsigned*)((const char*)(gbase) + (voff)[_i]), (LAS unsigned*)(lds + (bufoff) + ldsw + _i * 8192), 16, 0, 0); } while (0)
; #define PG8_LDA(dst, b, h) do { _Pragma("unroll") for (int m = 0; m < 4; ++m) _Pragma("unroll") for (int k = 0; k < 2; ++k) dst[m][k] = *(const LAS bf16x8*)(lds + PG8_SA(b, h) + aoff + m * 2048 + k * 1024); } while (0)
; #define PG8_LDB(dst, b, h) do { _Pragma("unroll") for (int n = 0; n < 2; ++n) _Pragma("unroll") for (int k = 0; k < 2; ++k) dst[n][k] = *(const LAS bf16x8*)(lds + PG8_SB(b, h) + boff + n * 2048 + k * 1024); } while (0)
; #define PG8_MMA(ai, bj, At, Bt) do { __builtin_amdgcn_s_setprio(1); _Pragma("unroll") for (int m = 0; m < 4; ++m) _Pragma("unroll") for (int n = 0; n < 2; ++n) _Pragma("unroll") for (int k = 0; k < 2; ++k) \
;         acc[ai][bj][m][n] = __builtin_amdgcn_mfma_f32_16x16x32_bf16(Bt[n][k], At[m][k], acc[ai][bj][m][n], 0, 0, 0); __builtin_amdgcn_s_setprio(0); } while (0)
; #define PG8_WAIT_V(n) asm volatile("s_waitcnt vmcnt(" #n ")" ::: "memory")
; #define PG8_WAIT_L(n) asm volatile("s_waitcnt lgkmcnt(" #n ")" ::: "memory")
; #define PG8_BAR __builtin_amdgcn_s_barrier()
; #define PG8_SCHED __builtin_amdgcn_sched_barrier(0)
; template <class Epi, class Sched>
; __device__ __forceinline__ void gemm_phase(LAS unsigned char* lds, const int K, const Sched& S, const Epi& E) {
;     ...
;         for (int t = 0; t < nt; t += 2) {
;             const bool last = (t == nt - 2);
;             const char* a1 = cA + (size_t)(t + 1) * kstep;
;             const char* a2 = last ? nA : cA + (size_t)(t + 2) * kstep; const char* b2 = last ? nB : cB + (size_t)(t + 2) * kstep;
;             const char* a3 = a2 + kstep; const char* b3 = b2 + kstep;
;             PG8_LDB(B0, 0, 0); PG8_LDB(B1, 0, 1); PG8_SCHED; PG8_LDA(At, 0, 0); PG8_STAGE(PG8_SA(1, 1), a1 + hstep, voffA);
;             PG8_WAIT_V(8); PG8_WAIT_L(0); PG8_BAR; PG8_MMA(0, 0, At, B0); PG8_MMA(0, 1, At, B1); PG8_BAR; PG8_SCHED;
;             PG8_LDA(At, 0, 1); PG8_STAGE(PG8_SB(0, 0), b2, voffB); PG8_STAGE(PG8_SB(0, 1), b2 + hstep, voffB); PG8_STAGE(PG8_SA(0, 0), a2, voffA);
;             PG8_WAIT_V(8); PG8_WAIT_L(0); PG8_BAR; PG8_MMA(1, 0, At, B0); PG8_MMA(1, 1, At, B1); PG8_BAR; PG8_SCHED;
.LBB0_533:
	s_add_u32 s14, s50, s11
	s_addc_u32 s15, s51, 0
	s_add_u32 s16, s14, 0x100
	s_addc_u32 s17, s15, 0
	s_and_b64 s[12:13], s[54:55], exec
	s_cselect_b32 s59, s45, s17
	s_cselect_b32 s58, s44, s16
	s_add_u32 s11, s8, s11
	s_addc_u32 s12, s9, 0
	s_add_u32 s11, s11, 0x100
	s_addc_u32 s16, s12, 0
	s_add_i32 s21, 0, 0x10000
	s_and_b64 s[12:13], s[54:55], exec
	s_cselect_b32 s61, s47, s16
	s_cselect_b32 s60, s46, s11
	s_add_i32 s25, 0, 0x14000
	s_add_u32 s64, s14, 0x10080
	s_addc_u32 s65, s15, 0
	s_add_i32 s19, s21, s3
	s_add_i32 m0, s26, 0xc000
	s_add_i32 s28, s26, 0xe000
	s_add_i32 s15, s19, 0x2000
	v_add_u32_e32 v146, s21, v148
	s_add_u32 s62, s60, 0x10000
	ds_read_b128 v[152:155], v146
	ds_read_b128 v[156:159], v146 offset:1024
	ds_read_b128 v[160:163], v146 offset:2048
	ds_read_b128 v[164:167], v146 offset:3072
	v_add_u32_e32 v146, s25, v148
	s_addc_u32 s63, s61, 0
	s_add_i32 s17, s25, s3
	ds_read_b128 v[184:187], v146
	ds_read_b128 v[188:191], v146 offset:1024
	ds_read_b128 v[192:195], v146 offset:2048
	ds_read_b128 v[196:199], v146 offset:3072
	s_add_i32 s16, s17, 0x2000
	s_add_i32 s14, 0, 0x18000
	s_add_i32 s13, 0, 0x1c000
	s_add_u32 s56, s58, 0x10000
	s_addc_u32 s57, s59, 0
	s_add_i32 s12, s14, s3
	s_add_i32 s11, s12, 0x2000
	s_add_u32 s54, s60, 0x10080
	s_addc_u32 s55, s61, 0
	s_add_i32 s25, s13, s3
	s_add_i32 s21, s25, 0x2000
	v_lshl_add_u64 v[146:147], s[64:65], 0, v[144:145]
	ds_read_b128 v[200:203], v150
	ds_read_b128 v[204:207], v150 offset:1024
	ds_read_b128 v[208:211], v150 offset:2048
	ds_read_b128 v[212:215], v150 offset:3072
	ds_read_b128 v[216:219], v150 offset:4096
	ds_read_b128 v[220:223], v150 offset:5120
	ds_read_b128 v[224:227], v150 offset:6144
	ds_read_b128 v[228:231], v150 offset:7168
	global_load_lds_dwordx4 v[146:147], off
	v_lshl_add_u64 v[146:147], s[64:65], 0, v[140:141]
	s_mov_b32 m0, s28
	s_nop 0
	global_load_lds_dwordx4 v[146:147], off
	s_waitcnt vmcnt(8)
	s_waitcnt lgkmcnt(0)
	s_setprio 1
	s_barrier
	v_mfma_f32_16x16x32_bf16 v[124:127], v[152:155], v[200:203], v[124:127]
	v_mfma_f32_16x16x32_bf16 v[120:123], v[160:163], v[200:203], v[120:123]
	v_mfma_f32_16x16x32_bf16 v[112:115], v[152:155], v[208:211], v[112:115]
	v_mfma_f32_16x16x32_bf16 v[104:107], v[160:163], v[208:211], v[104:107]
	v_mfma_f32_16x16x32_bf16 v[96:99], v[152:155], v[216:219], v[96:99]
	v_mfma_f32_16x16x32_bf16 v[88:91], v[160:163], v[216:219], v[88:91]
	v_mfma_f32_16x16x32_bf16 v[80:83], v[152:155], v[224:227], v[80:83]
	v_mfma_f32_16x16x32_bf16 v[72:75], v[160:163], v[224:227], v[72:75]
	s_setprio 0
	s_setprio 1
	v_mfma_f32_16x16x32_bf16 v[124:127], v[156:159], v[204:207], v[124:127]
	v_mfma_f32_16x16x32_bf16 v[120:123], v[164:167], v[204:207], v[120:123]
	v_mfma_f32_16x16x32_bf16 v[112:115], v[156:159], v[212:215], v[112:115]
	v_mfma_f32_16x16x32_bf16 v[104:107], v[164:167], v[212:215], v[104:107]
	v_mfma_f32_16x16x32_bf16 v[96:99], v[156:159], v[220:223], v[96:99]
	v_mfma_f32_16x16x32_bf16 v[88:91], v[164:167], v[220:223], v[88:91]
	v_mfma_f32_16x16x32_bf16 v[80:83], v[156:159], v[228:231], v[80:83]
	v_mfma_f32_16x16x32_bf16 v[72:75], v[164:167], v[228:231], v[72:75]
	s_setprio 0
	s_setprio 1
	v_mfma_f32_16x16x32_bf16 v[116:119], v[184:187], v[200:203], v[116:119]
	v_mfma_f32_16x16x32_bf16 v[108:111], v[192:195], v[200:203], v[108:111]
	v_mfma_f32_16x16x32_bf16 v[100:103], v[184:187], v[208:211], v[100:103]
	v_mfma_f32_16x16x32_bf16 v[92:95], v[192:195], v[208:211], v[92:95]
	v_mfma_f32_16x16x32_bf16 v[84:87], v[184:187], v[216:219], v[84:87]
	v_mfma_f32_16x16x32_bf16 v[76:79], v[192:195], v[216:219], v[76:79]
	v_mfma_f32_16x16x32_bf16 v[68:71], v[184:187], v[224:227], v[68:71]
	v_mfma_f32_16x16x32_bf16 v[64:67], v[192:195], v[224:227], v[64:67]
	s_setprio 0
	s_setprio 1
	v_mfma_f32_16x16x32_bf16 v[116:119], v[188:191], v[204:207], v[116:119]
	v_mfma_f32_16x16x32_bf16 v[108:111], v[196:199], v[204:207], v[108:111]
	v_mfma_f32_16x16x32_bf16 v[100:103], v[188:191], v[212:215], v[100:103]
	v_mfma_f32_16x16x32_bf16 v[92:95], v[196:199], v[212:215], v[92:95]
	v_mfma_f32_16x16x32_bf16 v[84:87], v[188:191], v[220:223], v[84:87]
	v_mfma_f32_16x16x32_bf16 v[76:79], v[196:199], v[220:223], v[76:79]
	v_mfma_f32_16x16x32_bf16 v[68:71], v[188:191], v[228:231], v[68:71]
	v_mfma_f32_16x16x32_bf16 v[64:67], v[196:199], v[228:231], v[64:67]
	s_barrier
	s_setprio 0
	s_mov_b32 m0, s19
	v_lshl_add_u64 v[146:147], s[60:61], 0, v[142:143]
	ds_read_b128 v[200:203], v150 offset:16384
	ds_read_b128 v[204:207], v150 offset:17408
	ds_read_b128 v[208:211], v150 offset:18432
	ds_read_b128 v[212:215], v150 offset:19456
	ds_read_b128 v[216:219], v150 offset:20480
	ds_read_b128 v[220:223], v150 offset:21504
	ds_read_b128 v[224:227], v150 offset:22528
	ds_read_b128 v[228:231], v150 offset:23552
	global_load_lds_dwordx4 v[146:147], off
	v_lshl_add_u64 v[180:181], s[60:61], 0, v[138:139]
	s_mov_b32 m0, s15
	v_lshl_add_u64 v[182:183], s[62:63], 0, v[142:143]
	global_load_lds_dwordx4 v[180:181], off
	s_mov_b32 m0, s17
	v_lshl_add_u64 v[232:233], s[58:59], 0, v[140:141]
	global_load_lds_dwordx4 v[182:183], off
	v_lshl_add_u64 v[182:183], s[62:63], 0, v[138:139]
	s_mov_b32 m0, s16
	s_nop 0
	global_load_lds_dwordx4 v[182:183], off
	v_lshl_add_u64 v[182:183], s[58:59], 0, v[144:145]
	s_mov_b32 m0, s26
	s_nop 0
	global_load_lds_dwordx4 v[182:183], off
	s_mov_b32 m0, s27
	s_nop 0
	global_load_lds_dwordx4 v[232:233], off
	s_waitcnt vmcnt(8)
	s_waitcnt lgkmcnt(0)
	s_setprio 1
	s_barrier
; #define PG8_STAGE(bufoff, gbase, voff) do { _Pragma("unroll") for (int _i = 0; _i < 2; ++_i) \
;         __builtin_amdgcn_global_load_lds((const unsigned*)((const char*)(gbase) + (voff)[_i]), (LAS unsigned*)(lds + (bufoff) + ldsw + _i * 8192), 16, 0, 0); } while (0)
; #define PG8_LDA(dst, b, h) do { _Pragma("unroll") for (int m = 0; m < 4; ++m) _Pragma("unroll") for (int k = 0; k < 2; ++k) dst[m][k] = *(const LAS bf16x8*)(lds + PG8_SA(b, h) + aoff + m * 2048 + k * 1024); } while (0)
; #define PG8_LDB(dst, b, h) do { _Pragma("unroll") for (int n = 0; n < 2; ++n) _Pragma("unroll") for (int k = 0; k < 2; ++k) dst[n][k] = *(const LAS bf16x8*)(lds + PG8_SB(b, h) + boff + n * 2048 + k * 1024); } while (0)
; #define PG8_MMA(ai, bj, At, Bt) do { __builtin_amdgcn_s_setprio(1); _Pragma("unroll") for (int m = 0; m < 4; ++m) _Pragma("unroll") for (int n = 0; n < 2; ++n) _Pragma("unroll") for (int k = 0; k < 2; ++k) \
;         acc[ai][bj][m][n] = __builtin_amdgcn_mfma_f32_16x16x32_bf16(Bt[n][k], At[m][k], acc[ai][bj][m][n], 0, 0, 0); __builtin_amdgcn_s_setprio(0); } while (0)
; #define PG8_WAIT_V(n) asm volatile("s_waitcnt vmcnt(" #n ")" ::: "memory")
; #define PG8_WAIT_L(n) asm volatile("s_waitcnt lgkmcnt(" #n ")" ::: "memory")
; #define PG8_BAR __builtin_amdgcn_s_barrier()
; #define PG8_SCHED __builtin_amdgcn_sched_barrier(0)
; template <class Epi, class Sched>
; __device__ __forceinline__ void gemm_phase(LAS unsigned char* lds, const int K, const Sched& S, const Epi& E) {
;     ...
;             PG8_WAIT_V(8); PG8_WAIT_L(0); PG8_BAR; PG8_MMA(1, 0, At, B0); PG8_MMA(1, 1, At, B1); PG8_BAR; PG8_SCHED;
;             PG8_LDB(B0, 1, 0); PG8_LDB(B1, 1, 1); PG8_SCHED; PG8_LDA(At, 1, 0); PG8_STAGE(PG8_SA(0, 1), a2 + hstep, voffA);
;             PG8_WAIT_V(8); PG8_WAIT_L(0); PG8_BAR; PG8_MMA(0, 0, At, B0); PG8_MMA(0, 1, At, B1); PG8_BAR; PG8_SCHED;
	v_mfma_f32_16x16x32_bf16 v[60:63], v[152:155], v[200:203], v[60:63]
	v_mfma_f32_16x16x32_bf16 v[56:59], v[160:163], v[200:203], v[56:59]
	v_mfma_f32_16x16x32_bf16 v[48:51], v[152:155], v[208:211], v[48:51]
	v_mfma_f32_16x16x32_bf16 v[40:43], v[160:163], v[208:211], v[40:43]
	v_mfma_f32_16x16x32_bf16 v[32:35], v[152:155], v[216:219], v[32:35]
	v_mfma_f32_16x16x32_bf16 v[24:27], v[160:163], v[216:219], v[24:27]
	v_mfma_f32_16x16x32_bf16 v[16:19], v[152:155], v[224:227], v[16:19]
	v_mfma_f32_16x16x32_bf16 v[8:11], v[160:163], v[224:227], v[8:11]
	s_setprio 0
	s_setprio 1
	v_mfma_f32_16x16x32_bf16 v[60:63], v[156:159], v[204:207], v[60:63]
	v_mfma_f32_16x16x32_bf16 v[56:59], v[164:167], v[204:207], v[56:59]
	v_mfma_f32_16x16x32_bf16 v[48:51], v[156:159], v[212:215], v[48:51]
	v_mfma_f32_16x16x32_bf16 v[40:43], v[164:167], v[212:215], v[40:43]
	v_mfma_f32_16x16x32_bf16 v[32:35], v[156:159], v[220:223], v[32:35]
	v_mfma_f32_16x16x32_bf16 v[24:27], v[164:167], v[220:223], v[24:27]
	v_mfma_f32_16x16x32_bf16 v[16:19], v[156:159], v[228:231], v[16:19]
	v_mfma_f32_16x16x32_bf16 v[8:11], v[164:167], v[228:231], v[8:11]
	s_setprio 0
	s_setprio 1
	v_mfma_f32_16x16x32_bf16 v[52:55], v[184:187], v[200:203], v[52:55]
	v_mfma_f32_16x16x32_bf16 v[44:47], v[192:195], v[200:203], v[44:47]
	v_mfma_f32_16x16x32_bf16 v[36:39], v[184:187], v[208:211], v[36:39]
	v_mfma_f32_16x16x32_bf16 v[28:31], v[192:195], v[208:211], v[28:31]
	v_mfma_f32_16x16x32_bf16 v[20:23], v[184:187], v[216:219], v[20:23]
	v_mfma_f32_16x16x32_bf16 v[12:15], v[192:195], v[216:219], v[12:15]
	v_mfma_f32_16x16x32_bf16 v[4:7], v[184:187], v[224:227], v[4:7]
	v_mfma_f32_16x16x32_bf16 v[0:3], v[192:195], v[224:227], v[0:3]
	s_setprio 0
	s_setprio 1
	v_mfma_f32_16x16x32_bf16 v[52:55], v[188:191], v[204:207], v[52:55]
	v_mfma_f32_16x16x32_bf16 v[44:47], v[196:199], v[204:207], v[44:47]
	v_mfma_f32_16x16x32_bf16 v[36:39], v[188:191], v[212:215], v[36:39]
	v_mfma_f32_16x16x32_bf16 v[28:31], v[196:199], v[212:215], v[28:31]
	v_mfma_f32_16x16x32_bf16 v[20:23], v[188:191], v[220:223], v[20:23]
	v_mfma_f32_16x16x32_bf16 v[12:15], v[196:199], v[220:223], v[12:15]
	v_mfma_f32_16x16x32_bf16 v[4:7], v[188:191], v[228:231], v[4:7]
	v_mfma_f32_16x16x32_bf16 v[0:3], v[196:199], v[228:231], v[0:3]
	s_barrier
	s_setprio 0
	v_add_u32_e32 v151, s14, v148
	ds_read_b128 v[152:155], v151
	ds_read_b128 v[156:159], v151 offset:1024
	ds_read_b128 v[160:163], v151 offset:2048
	ds_read_b128 v[164:167], v151 offset:3072
	v_add_u32_e32 v151, s13, v148
	ds_read_b128 v[184:187], v151
	ds_read_b128 v[188:191], v151 offset:1024
	ds_read_b128 v[192:195], v151 offset:2048
	ds_read_b128 v[196:199], v151 offset:3072
	s_mov_b32 m0, s66
	v_lshl_add_u64 v[234:235], s[56:57], 0, v[144:145]
	ds_read_b128 v[200:203], v150 offset:32768
	ds_read_b128 v[204:207], v150 offset:33792
	ds_read_b128 v[208:211], v150 offset:34816
	ds_read_b128 v[212:215], v150 offset:35840
	ds_read_b128 v[216:219], v150 offset:36864
	ds_read_b128 v[220:223], v150 offset:37888
	ds_read_b128 v[224:227], v150 offset:38912
	ds_read_b128 v[228:231], v150 offset:39936
	global_load_lds_dwordx4 v[234:235], off
	v_lshl_add_u64 v[234:235], s[56:57], 0, v[140:141]
	s_mov_b32 m0, s67
	s_nop 0
	global_load_lds_dwordx4 v[234:235], off
	s_waitcnt vmcnt(8)
	s_waitcnt lgkmcnt(0)
	s_setprio 1
	s_barrier
	v_mfma_f32_16x16x32_bf16 v[124:127], v[152:155], v[200:203], v[124:127]
	v_mfma_f32_16x16x32_bf16 v[120:123], v[160:163], v[200:203], v[120:123]
	v_mfma_f32_16x16x32_bf16 v[112:115], v[152:155], v[208:211], v[112:115]
	v_mfma_f32_16x16x32_bf16 v[104:107], v[160:163], v[208:211], v[104:107]
	v_mfma_f32_16x16x32_bf16 v[96:99], v[152:155], v[216:219], v[96:99]
	v_mfma_f32_16x16x32_bf16 v[88:91], v[160:163], v[216:219], v[88:91]
	v_mfma_f32_16x16x32_bf16 v[80:83], v[152:155], v[224:227], v[80:83]
	v_mfma_f32_16x16x32_bf16 v[72:75], v[160:163], v[224:227], v[72:75]
	s_setprio 0
	s_setprio 1
	v_mfma_f32_16x16x32_bf16 v[124:127], v[156:159], v[204:207], v[124:127]
	v_mfma_f32_16x16x32_bf16 v[120:123], v[164:167], v[204:207], v[120:123]
	v_mfma_f32_16x16x32_bf16 v[112:115], v[156:159], v[212:215], v[112:115]
	v_mfma_f32_16x16x32_bf16 v[104:107], v[164:167], v[212:215], v[104:107]
	v_mfma_f32_16x16x32_bf16 v[96:99], v[156:159], v[220:223], v[96:99]
	v_mfma_f32_16x16x32_bf16 v[88:91], v[164:167], v[220:223], v[88:91]
	v_mfma_f32_16x16x32_bf16 v[80:83], v[156:159], v[228:231], v[80:83]
	v_mfma_f32_16x16x32_bf16 v[72:75], v[164:167], v[228:231], v[72:75]
	s_setprio 0
	s_setprio 1
	v_mfma_f32_16x16x32_bf16 v[116:119], v[184:187], v[200:203], v[116:119]
	v_mfma_f32_16x16x32_bf16 v[108:111], v[192:195], v[200:203], v[108:111]
	v_mfma_f32_16x16x32_bf16 v[100:103], v[184:187], v[208:211], v[100:103]
	v_mfma_f32_16x16x32_bf16 v[92:95], v[192:195], v[208:211], v[92:95]
	v_mfma_f32_16x16x32_bf16 v[84:87], v[184:187], v[216:219], v[84:87]
	v_mfma_f32_16x16x32_bf16 v[76:79], v[192:195], v[216:219], v[76:79]
	v_mfma_f32_16x16x32_bf16 v[68:71], v[184:187], v[224:227], v[68:71]
	v_mfma_f32_16x16x32_bf16 v[64:67], v[192:195], v[224:227], v[64:67]
	s_setprio 0
	s_setprio 1
	v_mfma_f32_16x16x32_bf16 v[116:119], v[188:191], v[204:207], v[116:119]
	v_mfma_f32_16x16x32_bf16 v[108:111], v[196:199], v[204:207], v[108:111]
	v_mfma_f32_16x16x32_bf16 v[100:103], v[188:191], v[212:215], v[100:103]
	v_mfma_f32_16x16x32_bf16 v[92:95], v[196:199], v[212:215], v[92:95]
	v_mfma_f32_16x16x32_bf16 v[84:87], v[188:191], v[220:223], v[84:87]
	v_mfma_f32_16x16x32_bf16 v[76:79], v[196:199], v[220:223], v[76:79]
	v_mfma_f32_16x16x32_bf16 v[68:71], v[188:191], v[228:231], v[68:71]
	v_mfma_f32_16x16x32_bf16 v[64:67], v[196:199], v[228:231], v[64:67]
	s_barrier
; #define PG8_STAGE(bufoff, gbase, voff) do { _Pragma("unroll") for (int _i = 0; _i < 2; ++_i) \
;         __builtin_amdgcn_global_load_lds((const unsigned*)((const char*)(gbase) + (voff)[_i]), (LAS unsigned*)(lds + (bufoff) + ldsw + _i * 8192), 16, 0, 0); } while (0)
; #define PG8_LDA(dst, b, h) do { _Pragma("unroll") for (int m = 0; m < 4; ++m) _Pragma("unroll") for (int k = 0; k < 2; ++k) dst[m][k] = *(const LAS bf16x8*)(lds + PG8_SA(b, h) + aoff + m * 2048 + k * 1024); } while (0)
; #define PG8_MMA(ai, bj, At, Bt) do { __builtin_amdgcn_s_setprio(1); _Pragma("unroll") for (int m = 0; m < 4; ++m) _Pragma("unroll") for (int n = 0; n < 2; ++n) _Pragma("unroll") for (int k = 0; k < 2; ++k) \
;         acc[ai][bj][m][n] = __builtin_amdgcn_mfma_f32_16x16x32_bf16(Bt[n][k], At[m][k], acc[ai][bj][m][n], 0, 0, 0); __builtin_amdgcn_s_setprio(0); } while (0)
; #define PG8_WAIT_V(n) asm volatile("s_waitcnt vmcnt(" #n ")" ::: "memory")
; #define PG8_WAIT_L(n) asm volatile("s_waitcnt lgkmcnt(" #n ")" ::: "memory")
; #define PG8_BAR __builtin_amdgcn_s_barrier()
; #define PG8_SCHED __builtin_amdgcn_sched_barrier(0)
; template <class Epi, class Sched>
; __device__ __forceinline__ void gemm_phase(LAS unsigned char* lds, const int K, const Sched& S, const Epi& E) {
;     ...
;             PG8_LDA(At, 1, 1); PG8_STAGE(PG8_SB(1, 0), b3, voffB); PG8_STAGE(PG8_SB(1, 1), b3 + hstep, voffB); PG8_STAGE(PG8_SA(1, 0), a3, voffA);
;             PG8_WAIT_V(8); PG8_WAIT_L(0); PG8_BAR; PG8_MMA(1, 0, At, B0); PG8_MMA(1, 1, At, B1); PG8_BAR; PG8_SCHED;
;         }
;         if (wr == 0) PG8_BAR;
	s_setprio 0
	s_mov_b32 m0, s12
	v_lshl_add_u64 v[146:147], v[146:147], 0, s[36:37]
	ds_read_b128 v[200:203], v150 offset:49152
	ds_read_b128 v[204:207], v150 offset:50176
	ds_read_b128 v[208:211], v150 offset:51200
	ds_read_b128 v[212:215], v150 offset:52224
	ds_read_b128 v[216:219], v150 offset:53248
	ds_read_b128 v[220:223], v150 offset:54272
	ds_read_b128 v[224:227], v150 offset:55296
	ds_read_b128 v[228:231], v150 offset:56320
	global_load_lds_dwordx4 v[146:147], off
	v_lshl_add_u64 v[146:147], v[180:181], 0, s[36:37]
	s_mov_b32 m0, s11
	s_nop 0
	global_load_lds_dwordx4 v[146:147], off
	v_lshl_add_u64 v[146:147], s[54:55], 0, v[142:143]
	s_mov_b32 m0, s25
	s_nop 0
	global_load_lds_dwordx4 v[146:147], off
	v_lshl_add_u64 v[146:147], s[54:55], 0, v[138:139]
	s_mov_b32 m0, s21
	s_nop 0
	global_load_lds_dwordx4 v[146:147], off
	v_lshl_add_u64 v[146:147], v[182:183], 0, s[36:37]
	s_mov_b32 m0, s0
	s_nop 0
	global_load_lds_dwordx4 v[146:147], off
	v_lshl_add_u64 v[146:147], v[232:233], 0, s[36:37]
	s_mov_b32 m0, s1
	s_nop 0
	global_load_lds_dwordx4 v[146:147], off
	s_waitcnt vmcnt(8)
	s_waitcnt lgkmcnt(0)
	s_setprio 1
	s_barrier
	v_mfma_f32_16x16x32_bf16 v[60:63], v[152:155], v[200:203], v[60:63]
	v_mfma_f32_16x16x32_bf16 v[56:59], v[160:163], v[200:203], v[56:59]
	v_mfma_f32_16x16x32_bf16 v[48:51], v[152:155], v[208:211], v[48:51]
	v_mfma_f32_16x16x32_bf16 v[40:43], v[160:163], v[208:211], v[40:43]
	v_mfma_f32_16x16x32_bf16 v[32:35], v[152:155], v[216:219], v[32:35]
	v_mfma_f32_16x16x32_bf16 v[24:27], v[160:163], v[216:219], v[24:27]
	v_mfma_f32_16x16x32_bf16 v[16:19], v[152:155], v[224:227], v[16:19]
	v_mfma_f32_16x16x32_bf16 v[8:11], v[160:163], v[224:227], v[8:11]
	s_setprio 0
	s_setprio 1
	v_mfma_f32_16x16x32_bf16 v[60:63], v[156:159], v[204:207], v[60:63]
	v_mfma_f32_16x16x32_bf16 v[56:59], v[164:167], v[204:207], v[56:59]
	v_mfma_f32_16x16x32_bf16 v[48:51], v[156:159], v[212:215], v[48:51]
	v_mfma_f32_16x16x32_bf16 v[40:43], v[164:167], v[212:215], v[40:43]
	v_mfma_f32_16x16x32_bf16 v[32:35], v[156:159], v[220:223], v[32:35]
	v_mfma_f32_16x16x32_bf16 v[24:27], v[164:167], v[220:223], v[24:27]
	v_mfma_f32_16x16x32_bf16 v[16:19], v[156:159], v[228:231], v[16:19]
	v_mfma_f32_16x16x32_bf16 v[8:11], v[164:167], v[228:231], v[8:11]
	s_setprio 0
	s_setprio 1
	v_mfma_f32_16x16x32_bf16 v[52:55], v[184:187], v[200:203], v[52:55]
	v_mfma_f32_16x16x32_bf16 v[44:47], v[192:195], v[200:203], v[44:47]
	v_mfma_f32_16x16x32_bf16 v[36:39], v[184:187], v[208:211], v[36:39]
	v_mfma_f32_16x16x32_bf16 v[28:31], v[192:195], v[208:211], v[28:31]
	v_mfma_f32_16x16x32_bf16 v[20:23], v[184:187], v[216:219], v[20:23]
	v_mfma_f32_16x16x32_bf16 v[12:15], v[192:195], v[216:219], v[12:15]
	v_mfma_f32_16x16x32_bf16 v[4:7], v[184:187], v[224:227], v[4:7]
	v_mfma_f32_16x16x32_bf16 v[0:3], v[192:195], v[224:227], v[0:3]
	s_setprio 0
	s_setprio 1
	v_mfma_f32_16x16x32_bf16 v[52:55], v[188:191], v[204:207], v[52:55]
	v_mfma_f32_16x16x32_bf16 v[44:47], v[196:199], v[204:207], v[44:47]
	v_mfma_f32_16x16x32_bf16 v[36:39], v[188:191], v[212:215], v[36:39]
	v_mfma_f32_16x16x32_bf16 v[28:31], v[196:199], v[212:215], v[28:31]
	v_mfma_f32_16x16x32_bf16 v[20:23], v[188:191], v[220:223], v[20:23]
	v_mfma_f32_16x16x32_bf16 v[12:15], v[196:199], v[220:223], v[12:15]
	v_mfma_f32_16x16x32_bf16 v[4:7], v[188:191], v[228:231], v[4:7]
	v_mfma_f32_16x16x32_bf16 v[0:3], v[196:199], v[228:231], v[0:3]
	s_barrier
	s_setprio 0
	s_movk_i32 s11, 0x100
	s_andn2_b64 vcc, exec, s[52:53]
	s_mov_b64 s[54:55], -1
	s_mov_b64 s[52:53], 0
	s_cbranch_vccz .LBB0_533
	s_and_b64 vcc, exec, s[40:41]
	s_cbranch_vccz .LBB0_536
	s_barrier

; #define PG8_STAGE(bufoff, gbase, voff) do { _Pragma("unroll") for (int _i = 0; _i < 2; ++_i) \
;         __builtin_amdgcn_global_load_lds((const unsigned*)((const char*)(gbase) + (voff)[_i]), (LAS unsigned*)(lds + (bufoff) + ldsw + _i * 8192), 16, 0, 0); } while (0)
; #define PG8_LDA(dst, b, h) do { _Pragma("unroll") for (int m = 0; m < 4; ++m) _Pragma("unroll") for (int k = 0; k < 2; ++k) dst[m][k] = *(const LAS bf16x8*)(lds + PG8_SA(b, h) + aoff + m * 2048 + k * 1024); } while (0)
; #define PG8_LDB(dst, b, h) do { _Pragma("unroll") for (int n = 0; n < 2; ++n) _Pragma("unroll") for (int k = 0; k < 2; ++k) dst[n][k] = *(const LAS bf16x8*)(lds + PG8_SB(b, h) + boff + n * 2048 + k * 1024); } while (0)
; #define PG8_MMA(ai, bj, At, Bt) do { __builtin_amdgcn_s_setprio(1); _Pragma("unroll") for (int m = 0; m < 4; ++m) _Pragma("unroll") for (int n = 0; n < 2; ++n) _Pragma("unroll") for (int k = 0; k < 2; ++k) \
;         acc[ai][bj][m][n] = __builtin_amdgcn_mfma_f32_16x16x32_bf16(Bt[n][k], At[m][k], acc[ai][bj][m][n], 0, 0, 0); __builtin_amdgcn_s_setprio(0); } while (0)
; #define PG8_WAIT_V(n) asm volatile("s_waitcnt vmcnt(" #n ")" ::: "memory")
; #define PG8_WAIT_L(n) asm volatile("s_waitcnt lgkmcnt(" #n ")" ::: "memory")
; #define PG8_BAR __builtin_amdgcn_s_barrier()
; #define PG8_SCHED __builtin_amdgcn_sched_barrier(0)
; template <class Epi, class Sched>
; __device__ __forceinline__ void gemm_phase(LAS unsigned char* lds, const int K, const Sched& S, const Epi& E) {
;     ...
;         for (int t = 0; t < nt; t += 2) {
;             const bool last = (t == nt - 2);
;             const char* a1 = cA + (size_t)(t + 1) * kstep;
;             const char* a2 = last ? nA : cA + (size_t)(t + 2) * kstep; const char* b2 = last ? nB : cB + (size_t)(t + 2) * kstep;
;             const char* a3 = a2 + kstep; const char* b3 = b2 + kstep;
;             PG8_LDB(B0, 0, 0); PG8_LDB(B1, 0, 1); PG8_SCHED; PG8_LDA(At, 0, 0); PG8_STAGE(PG8_SA(1, 1), a1 + hstep, voffA);
;             PG8_WAIT_V(8); PG8_WAIT_L(0); PG8_BAR; PG8_MMA(0, 0, At, B0); PG8_MMA(0, 1, At, B1); PG8_BAR; PG8_SCHED;
;             PG8_LDA(At, 0, 1); PG8_STAGE(PG8_SB(0, 0), b2, voffB); PG8_STAGE(PG8_SB(0, 1), b2 + hstep, voffB); PG8_STAGE(PG8_SA(0, 0), a2, voffA);
;             PG8_WAIT_V(8); PG8_WAIT_L(0); PG8_BAR; PG8_MMA(1, 0, At, B0); PG8_MMA(1, 1, At, B1); PG8_BAR; PG8_SCHED;
.LBB0_812:
	s_add_i32 s16, s15, 2
	s_add_u32 s50, s8, 0x100
	s_addc_u32 s51, s9, 0
	s_add_i32 s17, 0, 0x10000
	s_cmp_eq_u32 s12, s15
	s_cselect_b32 s55, s4, s51
	s_cselect_b32 s54, s5, s50
	s_cselect_b32 s53, s10, s14
	s_cselect_b32 s52, s11, s13
	s_add_i32 s15, 0, 0x14000
	v_add_u32_e32 v158, s17, v164
	v_add_u32_e32 v162, s15, v164
	ds_read_b128 v[146:149], v158
	ds_read_b128 v[150:153], v158 offset:1024
	ds_read_b128 v[154:157], v158 offset:2048
	ds_read_b128 v[158:161], v158 offset:3072
	ds_read_b128 v[184:187], v162
	ds_read_b128 v[188:191], v162 offset:1024
	ds_read_b128 v[192:195], v162 offset:2048
	ds_read_b128 v[196:199], v162 offset:3072
	v_lshl_add_u64 v[162:163], s[8:9], 0, v[142:143]
	s_add_i32 m0, s26, 0xc000
	ds_read_b128 v[200:203], v166
	ds_read_b128 v[204:207], v166 offset:1024
	ds_read_b128 v[208:211], v166 offset:2048
	ds_read_b128 v[212:215], v166 offset:3072
	ds_read_b128 v[216:219], v166 offset:4096
	ds_read_b128 v[220:223], v166 offset:5120
	ds_read_b128 v[224:227], v166 offset:6144
	ds_read_b128 v[228:231], v166 offset:7168
	global_load_lds_dwordx4 v[162:163], off
	v_lshl_add_u64 v[162:163], s[8:9], 0, v[144:145]
	s_add_i32 m0, s26, 0xe000
	s_nop 0
	global_load_lds_dwordx4 v[162:163], off
	s_waitcnt vmcnt(8)
	s_waitcnt lgkmcnt(0)
	s_setprio 1
	s_barrier
	v_mfma_f32_16x16x32_bf16 v[124:127], v[146:149], v[200:203], v[124:127]
	v_mfma_f32_16x16x32_bf16 v[92:95], v[154:157], v[200:203], v[92:95]
	v_mfma_f32_16x16x32_bf16 v[120:123], v[146:149], v[208:211], v[120:123]
	v_mfma_f32_16x16x32_bf16 v[88:91], v[154:157], v[208:211], v[88:91]
	v_mfma_f32_16x16x32_bf16 v[116:119], v[146:149], v[216:219], v[116:119]
	v_mfma_f32_16x16x32_bf16 v[84:87], v[154:157], v[216:219], v[84:87]
	v_mfma_f32_16x16x32_bf16 v[112:115], v[146:149], v[224:227], v[112:115]
	v_mfma_f32_16x16x32_bf16 v[80:83], v[154:157], v[224:227], v[80:83]
	s_setprio 0
	s_setprio 1
	v_mfma_f32_16x16x32_bf16 v[124:127], v[150:153], v[204:207], v[124:127]
	v_mfma_f32_16x16x32_bf16 v[92:95], v[158:161], v[204:207], v[92:95]
	v_mfma_f32_16x16x32_bf16 v[120:123], v[150:153], v[212:215], v[120:123]
	v_mfma_f32_16x16x32_bf16 v[88:91], v[158:161], v[212:215], v[88:91]
	v_mfma_f32_16x16x32_bf16 v[116:119], v[150:153], v[220:223], v[116:119]
	v_mfma_f32_16x16x32_bf16 v[84:87], v[158:161], v[220:223], v[84:87]
	v_mfma_f32_16x16x32_bf16 v[112:115], v[150:153], v[228:231], v[112:115]
	v_mfma_f32_16x16x32_bf16 v[80:83], v[158:161], v[228:231], v[80:83]
	s_setprio 0
	s_setprio 1
	v_mfma_f32_16x16x32_bf16 v[64:67], v[184:187], v[200:203], v[64:67]
	v_mfma_f32_16x16x32_bf16 v[40:43], v[192:195], v[200:203], v[40:43]
	v_mfma_f32_16x16x32_bf16 v[56:59], v[184:187], v[208:211], v[56:59]
	v_mfma_f32_16x16x32_bf16 v[32:35], v[192:195], v[208:211], v[32:35]
	v_mfma_f32_16x16x32_bf16 v[52:55], v[184:187], v[216:219], v[52:55]
	v_mfma_f32_16x16x32_bf16 v[24:27], v[192:195], v[216:219], v[24:27]
	v_mfma_f32_16x16x32_bf16 v[48:51], v[184:187], v[224:227], v[48:51]
	v_mfma_f32_16x16x32_bf16 v[16:19], v[192:195], v[224:227], v[16:19]
	s_setprio 0
	s_setprio 1
	v_mfma_f32_16x16x32_bf16 v[64:67], v[188:191], v[204:207], v[64:67]
	v_mfma_f32_16x16x32_bf16 v[40:43], v[196:199], v[204:207], v[40:43]
	v_mfma_f32_16x16x32_bf16 v[56:59], v[188:191], v[212:215], v[56:59]
	v_mfma_f32_16x16x32_bf16 v[32:35], v[196:199], v[212:215], v[32:35]
	v_mfma_f32_16x16x32_bf16 v[52:55], v[188:191], v[220:223], v[52:55]
	v_mfma_f32_16x16x32_bf16 v[24:27], v[196:199], v[220:223], v[24:27]
	v_mfma_f32_16x16x32_bf16 v[48:51], v[188:191], v[228:231], v[48:51]
	v_mfma_f32_16x16x32_bf16 v[16:19], v[196:199], v[228:231], v[16:19]
	s_barrier
	s_setprio 0
	s_add_i32 s8, s17, s3
	v_lshl_add_u64 v[162:163], s[52:53], 0, v[128:129]
	s_mov_b32 m0, s8
	ds_read_b128 v[200:203], v166 offset:16384
	ds_read_b128 v[204:207], v166 offset:17408
	ds_read_b128 v[208:211], v166 offset:18432
	ds_read_b128 v[212:215], v166 offset:19456
	ds_read_b128 v[216:219], v166 offset:20480
	ds_read_b128 v[220:223], v166 offset:21504
	ds_read_b128 v[224:227], v166 offset:22528
	ds_read_b128 v[228:231], v166 offset:23552
	global_load_lds_dwordx4 v[162:163], off
	s_add_i32 m0, s8, 0x2000
	s_add_u32 s8, s52, 0x50000
	v_lshl_add_u64 v[180:181], s[52:53], 0, v[138:139]
	s_addc_u32 s9, s53, 0
	s_add_i32 s15, s15, s3
	global_load_lds_dwordx4 v[180:181], off
	v_lshl_add_u64 v[182:183], s[8:9], 0, v[128:129]
	s_mov_b32 m0, s15
	v_lshl_add_u64 v[232:233], s[54:55], 0, v[138:139]
	global_load_lds_dwordx4 v[182:183], off
	v_lshl_add_u64 v[182:183], s[8:9], 0, v[138:139]
	s_add_i32 m0, s15, 0x2000
	s_nop 0
	global_load_lds_dwordx4 v[182:183], off
	v_lshl_add_u64 v[182:183], s[54:55], 0, v[128:129]
	s_mov_b32 m0, s26
	s_nop 0
	global_load_lds_dwordx4 v[182:183], off
	s_mov_b32 m0, s27
	s_nop 0
	global_load_lds_dwordx4 v[232:233], off
	s_waitcnt vmcnt(8)
	s_waitcnt lgkmcnt(0)
	s_setprio 1
	s_barrier
; #define PG8_STAGE(bufoff, gbase, voff) do { _Pragma("unroll") for (int _i = 0; _i < 2; ++_i) \
;         __builtin_amdgcn_global_load_lds((const unsigned*)((const char*)(gbase) + (voff)[_i]), (LAS unsigned*)(lds + (bufoff) + ldsw + _i * 8192), 16, 0, 0); } while (0)
; #define PG8_LDA(dst, b, h) do { _Pragma("unroll") for (int m = 0; m < 4; ++m) _Pragma("unroll") for (int k = 0; k < 2; ++k) dst[m][k] = *(const LAS bf16x8*)(lds + PG8_SA(b, h) + aoff + m * 2048 + k * 1024); } while (0)
; #define PG8_LDB(dst, b, h) do { _Pragma("unroll") for (int n = 0; n < 2; ++n) _Pragma("unroll") for (int k = 0; k < 2; ++k) dst[n][k] = *(const LAS bf16x8*)(lds + PG8_SB(b, h) + boff + n * 2048 + k * 1024); } while (0)
; #define PG8_MMA(ai, bj, At, Bt) do { __builtin_amdgcn_s_setprio(1); _Pragma("unroll") for (int m = 0; m < 4; ++m) _Pragma("unroll") for (int n = 0; n < 2; ++n) _Pragma("unroll") for (int k = 0; k < 2; ++k) \
;         acc[ai][bj][m][n] = __builtin_amdgcn_mfma_f32_16x16x32_bf16(Bt[n][k], At[m][k], acc[ai][bj][m][n], 0, 0, 0); __builtin_amdgcn_s_setprio(0); } while (0)
; #define PG8_WAIT_V(n) asm volatile("s_waitcnt vmcnt(" #n ")" ::: "memory")
; #define PG8_WAIT_L(n) asm volatile("s_waitcnt lgkmcnt(" #n ")" ::: "memory")
; #define PG8_BAR __builtin_amdgcn_s_barrier()
; #define PG8_SCHED __builtin_amdgcn_sched_barrier(0)
; template <class Epi, class Sched>
; __device__ __forceinline__ void gemm_phase(LAS unsigned char* lds, const int K, const Sched& S, const Epi& E) {
;     ...
;             PG8_WAIT_V(8); PG8_WAIT_L(0); PG8_BAR; PG8_MMA(1, 0, At, B0); PG8_MMA(1, 1, At, B1); PG8_BAR; PG8_SCHED;
;             PG8_LDB(B0, 1, 0); PG8_LDB(B1, 1, 1); PG8_SCHED; PG8_LDA(At, 1, 0); PG8_STAGE(PG8_SA(0, 1), a2 + hstep, voffA);
;             PG8_WAIT_V(8); PG8_WAIT_L(0); PG8_BAR; PG8_MMA(0, 0, At, B0); PG8_MMA(0, 1, At, B1); PG8_BAR; PG8_SCHED;
	v_mfma_f32_16x16x32_bf16 v[108:111], v[146:149], v[200:203], v[108:111]
	v_mfma_f32_16x16x32_bf16 v[76:79], v[154:157], v[200:203], v[76:79]
	v_mfma_f32_16x16x32_bf16 v[104:107], v[146:149], v[208:211], v[104:107]
	v_mfma_f32_16x16x32_bf16 v[72:75], v[154:157], v[208:211], v[72:75]
	v_mfma_f32_16x16x32_bf16 v[100:103], v[146:149], v[216:219], v[100:103]
	v_mfma_f32_16x16x32_bf16 v[68:71], v[154:157], v[216:219], v[68:71]
	v_mfma_f32_16x16x32_bf16 v[96:99], v[146:149], v[224:227], v[96:99]
	v_mfma_f32_16x16x32_bf16 v[60:63], v[154:157], v[224:227], v[60:63]
	s_setprio 0
	s_setprio 1
	v_mfma_f32_16x16x32_bf16 v[108:111], v[150:153], v[204:207], v[108:111]
	v_mfma_f32_16x16x32_bf16 v[76:79], v[158:161], v[204:207], v[76:79]
	v_mfma_f32_16x16x32_bf16 v[104:107], v[150:153], v[212:215], v[104:107]
	v_mfma_f32_16x16x32_bf16 v[72:75], v[158:161], v[212:215], v[72:75]
	v_mfma_f32_16x16x32_bf16 v[100:103], v[150:153], v[220:223], v[100:103]
	v_mfma_f32_16x16x32_bf16 v[68:71], v[158:161], v[220:223], v[68:71]
	v_mfma_f32_16x16x32_bf16 v[96:99], v[150:153], v[228:231], v[96:99]
	v_mfma_f32_16x16x32_bf16 v[60:63], v[158:161], v[228:231], v[60:63]
	s_setprio 0
	s_setprio 1
	v_mfma_f32_16x16x32_bf16 v[44:47], v[184:187], v[200:203], v[44:47]
	v_mfma_f32_16x16x32_bf16 v[12:15], v[192:195], v[200:203], v[12:15]
	v_mfma_f32_16x16x32_bf16 v[36:39], v[184:187], v[208:211], v[36:39]
	v_mfma_f32_16x16x32_bf16 v[8:11], v[192:195], v[208:211], v[8:11]
	v_mfma_f32_16x16x32_bf16 v[28:31], v[184:187], v[216:219], v[28:31]
	v_mfma_f32_16x16x32_bf16 v[4:7], v[192:195], v[216:219], v[4:7]
	v_mfma_f32_16x16x32_bf16 v[20:23], v[184:187], v[224:227], v[20:23]
	v_mfma_f32_16x16x32_bf16 v[0:3], v[192:195], v[224:227], v[0:3]
	s_setprio 0
	s_setprio 1
	v_mfma_f32_16x16x32_bf16 v[44:47], v[188:191], v[204:207], v[44:47]
	v_mfma_f32_16x16x32_bf16 v[12:15], v[196:199], v[204:207], v[12:15]
	v_mfma_f32_16x16x32_bf16 v[36:39], v[188:191], v[212:215], v[36:39]
	v_mfma_f32_16x16x32_bf16 v[8:11], v[196:199], v[212:215], v[8:11]
	v_mfma_f32_16x16x32_bf16 v[28:31], v[188:191], v[220:223], v[28:31]
	v_mfma_f32_16x16x32_bf16 v[4:7], v[196:199], v[220:223], v[4:7]
	v_mfma_f32_16x16x32_bf16 v[20:23], v[188:191], v[228:231], v[20:23]
	v_mfma_f32_16x16x32_bf16 v[0:3], v[196:199], v[228:231], v[0:3]
	s_barrier
	s_setprio 0
	s_add_i32 s15, 0, 0x18000
	s_add_i32 s17, 0, 0x1c000
	v_add_u32_e32 v158, s15, v164
	v_add_u32_e32 v167, s17, v164
	ds_read_b128 v[146:149], v158
	ds_read_b128 v[150:153], v158 offset:1024
	ds_read_b128 v[154:157], v158 offset:2048
	ds_read_b128 v[158:161], v158 offset:3072
	ds_read_b128 v[184:187], v167
	ds_read_b128 v[188:191], v167 offset:1024
	ds_read_b128 v[192:195], v167 offset:2048
	ds_read_b128 v[196:199], v167 offset:3072
	s_add_u32 s8, s54, 0x50000
	s_addc_u32 s9, s55, 0
	s_mov_b32 m0, s56
	v_lshl_add_u64 v[234:235], s[8:9], 0, v[128:129]
	ds_read_b128 v[200:203], v166 offset:32768
	ds_read_b128 v[204:207], v166 offset:33792
	ds_read_b128 v[208:211], v166 offset:34816
	ds_read_b128 v[212:215], v166 offset:35840
	ds_read_b128 v[216:219], v166 offset:36864
	ds_read_b128 v[220:223], v166 offset:37888
	ds_read_b128 v[224:227], v166 offset:38912
	ds_read_b128 v[228:231], v166 offset:39936
	global_load_lds_dwordx4 v[234:235], off
	v_lshl_add_u64 v[234:235], s[8:9], 0, v[138:139]
	s_mov_b32 m0, s57
	s_nop 0
	global_load_lds_dwordx4 v[234:235], off
	s_waitcnt vmcnt(8)
	s_waitcnt lgkmcnt(0)
	s_setprio 1
	s_barrier
	v_mfma_f32_16x16x32_bf16 v[124:127], v[146:149], v[200:203], v[124:127]
	v_mfma_f32_16x16x32_bf16 v[92:95], v[154:157], v[200:203], v[92:95]
	v_mfma_f32_16x16x32_bf16 v[120:123], v[146:149], v[208:211], v[120:123]
	v_mfma_f32_16x16x32_bf16 v[88:91], v[154:157], v[208:211], v[88:91]
	v_mfma_f32_16x16x32_bf16 v[116:119], v[146:149], v[216:219], v[116:119]
	v_mfma_f32_16x16x32_bf16 v[84:87], v[154:157], v[216:219], v[84:87]
	v_mfma_f32_16x16x32_bf16 v[112:115], v[146:149], v[224:227], v[112:115]
	v_mfma_f32_16x16x32_bf16 v[80:83], v[154:157], v[224:227], v[80:83]
	s_setprio 0
	s_setprio 1
	v_mfma_f32_16x16x32_bf16 v[124:127], v[150:153], v[204:207], v[124:127]
	v_mfma_f32_16x16x32_bf16 v[92:95], v[158:161], v[204:207], v[92:95]
	v_mfma_f32_16x16x32_bf16 v[120:123], v[150:153], v[212:215], v[120:123]
	v_mfma_f32_16x16x32_bf16 v[88:91], v[158:161], v[212:215], v[88:91]
	v_mfma_f32_16x16x32_bf16 v[116:119], v[150:153], v[220:223], v[116:119]
	v_mfma_f32_16x16x32_bf16 v[84:87], v[158:161], v[220:223], v[84:87]
	v_mfma_f32_16x16x32_bf16 v[112:115], v[150:153], v[228:231], v[112:115]
	v_mfma_f32_16x16x32_bf16 v[80:83], v[158:161], v[228:231], v[80:83]
	s_setprio 0
	s_setprio 1
	v_mfma_f32_16x16x32_bf16 v[64:67], v[184:187], v[200:203], v[64:67]
	v_mfma_f32_16x16x32_bf16 v[40:43], v[192:195], v[200:203], v[40:43]
	v_mfma_f32_16x16x32_bf16 v[56:59], v[184:187], v[208:211], v[56:59]
	v_mfma_f32_16x16x32_bf16 v[32:35], v[192:195], v[208:211], v[32:35]
	v_mfma_f32_16x16x32_bf16 v[52:55], v[184:187], v[216:219], v[52:55]
	v_mfma_f32_16x16x32_bf16 v[24:27], v[192:195], v[216:219], v[24:27]
	v_mfma_f32_16x16x32_bf16 v[48:51], v[184:187], v[224:227], v[48:51]
	v_mfma_f32_16x16x32_bf16 v[16:19], v[192:195], v[224:227], v[16:19]
	s_setprio 0
	s_setprio 1
	v_mfma_f32_16x16x32_bf16 v[64:67], v[188:191], v[204:207], v[64:67]
	v_mfma_f32_16x16x32_bf16 v[40:43], v[196:199], v[204:207], v[40:43]
	v_mfma_f32_16x16x32_bf16 v[56:59], v[188:191], v[212:215], v[56:59]
	v_mfma_f32_16x16x32_bf16 v[32:35], v[196:199], v[212:215], v[32:35]
	v_mfma_f32_16x16x32_bf16 v[52:55], v[188:191], v[220:223], v[52:55]
	v_mfma_f32_16x16x32_bf16 v[24:27], v[196:199], v[220:223], v[24:27]
	v_mfma_f32_16x16x32_bf16 v[48:51], v[188:191], v[228:231], v[48:51]
	v_mfma_f32_16x16x32_bf16 v[16:19], v[196:199], v[228:231], v[16:19]
	s_barrier
; #define PG8_STAGE(bufoff, gbase, voff) do { _Pragma("unroll") for (int _i = 0; _i < 2; ++_i) \
;         __builtin_amdgcn_global_load_lds((const unsigned*)((const char*)(gbase) + (voff)[_i]), (LAS unsigned*)(lds + (bufoff) + ldsw + _i * 8192), 16, 0, 0); } while (0)
; #define PG8_LDA(dst, b, h) do { _Pragma("unroll") for (int m = 0; m < 4; ++m) _Pragma("unroll") for (int k = 0; k < 2; ++k) dst[m][k] = *(const LAS bf16x8*)(lds + PG8_SA(b, h) + aoff + m * 2048 + k * 1024); } while (0)
; #define PG8_MMA(ai, bj, At, Bt) do { __builtin_amdgcn_s_setprio(1); _Pragma("unroll") for (int m = 0; m < 4; ++m) _Pragma("unroll") for (int n = 0; n < 2; ++n) _Pragma("unroll") for (int k = 0; k < 2; ++k) \
;         acc[ai][bj][m][n] = __builtin_amdgcn_mfma_f32_16x16x32_bf16(Bt[n][k], At[m][k], acc[ai][bj][m][n], 0, 0, 0); __builtin_amdgcn_s_setprio(0); } while (0)
; #define PG8_WAIT_V(n) asm volatile("s_waitcnt vmcnt(" #n ")" ::: "memory")
; #define PG8_WAIT_L(n) asm volatile("s_waitcnt lgkmcnt(" #n ")" ::: "memory")
; #define PG8_BAR __builtin_amdgcn_s_barrier()
; #define PG8_SCHED __builtin_amdgcn_sched_barrier(0)
; template <class Epi, class Sched>
; __device__ __forceinline__ void gemm_phase(LAS unsigned char* lds, const int K, const Sched& S, const Epi& E) {
;     ...
;             PG8_LDA(At, 1, 1); PG8_STAGE(PG8_SB(1, 0), b3, voffB); PG8_STAGE(PG8_SB(1, 1), b3 + hstep, voffB); PG8_STAGE(PG8_SA(1, 0), a3, voffA);
;             PG8_WAIT_V(8); PG8_WAIT_L(0); PG8_BAR; PG8_MMA(1, 0, At, B0); PG8_MMA(1, 1, At, B1); PG8_BAR; PG8_SCHED;
;         }
;         if (wr == 0) PG8_BAR;
	s_setprio 0
	s_add_i32 s8, s15, s3
	v_lshl_add_u64 v[162:163], v[162:163], 0, s[36:37]
	s_mov_b32 m0, s8
	ds_read_b128 v[200:203], v166 offset:49152
	ds_read_b128 v[204:207], v166 offset:50176
	ds_read_b128 v[208:211], v166 offset:51200
	ds_read_b128 v[212:215], v166 offset:52224
	ds_read_b128 v[216:219], v166 offset:53248
	ds_read_b128 v[220:223], v166 offset:54272
	ds_read_b128 v[224:227], v166 offset:55296
	ds_read_b128 v[228:231], v166 offset:56320
	global_load_lds_dwordx4 v[162:163], off
	s_add_i32 m0, s8, 0x2000
	s_add_u32 s8, s52, 0x50080
	v_lshl_add_u64 v[162:163], v[180:181], 0, s[36:37]
	s_addc_u32 s9, s53, 0
	s_add_i32 s15, s17, s3
	global_load_lds_dwordx4 v[162:163], off
	v_lshl_add_u64 v[162:163], s[8:9], 0, v[128:129]
	s_mov_b32 m0, s15
	s_nop 0
	global_load_lds_dwordx4 v[162:163], off
	v_lshl_add_u64 v[162:163], s[8:9], 0, v[138:139]
	s_add_i32 m0, s15, 0x2000
	s_nop 0
	global_load_lds_dwordx4 v[162:163], off
	v_lshl_add_u64 v[162:163], v[182:183], 0, s[36:37]
	s_mov_b32 m0, s58
	s_nop 0
	global_load_lds_dwordx4 v[162:163], off
	v_lshl_add_u64 v[162:163], v[232:233], 0, s[36:37]
	s_mov_b32 m0, s59
	s_nop 0
	global_load_lds_dwordx4 v[162:163], off
	s_waitcnt vmcnt(8)
	s_waitcnt lgkmcnt(0)
	s_setprio 1
	s_barrier
	v_mfma_f32_16x16x32_bf16 v[108:111], v[146:149], v[200:203], v[108:111]
	v_mfma_f32_16x16x32_bf16 v[76:79], v[154:157], v[200:203], v[76:79]
	v_mfma_f32_16x16x32_bf16 v[104:107], v[146:149], v[208:211], v[104:107]
	v_mfma_f32_16x16x32_bf16 v[72:75], v[154:157], v[208:211], v[72:75]
	v_mfma_f32_16x16x32_bf16 v[100:103], v[146:149], v[216:219], v[100:103]
	v_mfma_f32_16x16x32_bf16 v[68:71], v[154:157], v[216:219], v[68:71]
	v_mfma_f32_16x16x32_bf16 v[96:99], v[146:149], v[224:227], v[96:99]
	v_mfma_f32_16x16x32_bf16 v[60:63], v[154:157], v[224:227], v[60:63]
	s_setprio 0
	s_setprio 1
	v_mfma_f32_16x16x32_bf16 v[108:111], v[150:153], v[204:207], v[108:111]
	v_mfma_f32_16x16x32_bf16 v[76:79], v[158:161], v[204:207], v[76:79]
	v_mfma_f32_16x16x32_bf16 v[104:107], v[150:153], v[212:215], v[104:107]
	v_mfma_f32_16x16x32_bf16 v[72:75], v[158:161], v[212:215], v[72:75]
	v_mfma_f32_16x16x32_bf16 v[100:103], v[150:153], v[220:223], v[100:103]
	v_mfma_f32_16x16x32_bf16 v[68:71], v[158:161], v[220:223], v[68:71]
	v_mfma_f32_16x16x32_bf16 v[96:99], v[150:153], v[228:231], v[96:99]
	v_mfma_f32_16x16x32_bf16 v[60:63], v[158:161], v[228:231], v[60:63]
	s_setprio 0
	s_setprio 1
	v_mfma_f32_16x16x32_bf16 v[44:47], v[184:187], v[200:203], v[44:47]
	v_mfma_f32_16x16x32_bf16 v[12:15], v[192:195], v[200:203], v[12:15]
	v_mfma_f32_16x16x32_bf16 v[36:39], v[184:187], v[208:211], v[36:39]
	v_mfma_f32_16x16x32_bf16 v[8:11], v[192:195], v[208:211], v[8:11]
	v_mfma_f32_16x16x32_bf16 v[28:31], v[184:187], v[216:219], v[28:31]
	v_mfma_f32_16x16x32_bf16 v[4:7], v[192:195], v[216:219], v[4:7]
	v_mfma_f32_16x16x32_bf16 v[20:23], v[184:187], v[224:227], v[20:23]
	v_mfma_f32_16x16x32_bf16 v[0:3], v[192:195], v[224:227], v[0:3]
	s_setprio 0
	s_setprio 1
	v_mfma_f32_16x16x32_bf16 v[44:47], v[188:191], v[204:207], v[44:47]
	v_mfma_f32_16x16x32_bf16 v[12:15], v[196:199], v[204:207], v[12:15]
	v_mfma_f32_16x16x32_bf16 v[36:39], v[188:191], v[212:215], v[36:39]
	v_mfma_f32_16x16x32_bf16 v[8:11], v[196:199], v[212:215], v[8:11]
	v_mfma_f32_16x16x32_bf16 v[28:31], v[188:191], v[220:223], v[28:31]
	v_mfma_f32_16x16x32_bf16 v[4:7], v[196:199], v[220:223], v[4:7]
	v_mfma_f32_16x16x32_bf16 v[20:23], v[188:191], v[228:231], v[20:23]
	v_mfma_f32_16x16x32_bf16 v[0:3], v[196:199], v[228:231], v[0:3]
	s_barrier
	s_setprio 0
	s_add_u32 s13, s13, 0x100
	s_addc_u32 s14, s14, 0
	s_cmp_ge_i32 s16, s2
	s_mov_b64 s[8:9], s[50:51]
	s_mov_b32 s15, s16
	s_cbranch_scc0 .LBB0_812
	s_and_b64 vcc, exec, s[40:41]
	s_cbranch_vccz .LBB0_815
	s_barrier

; #define PG8_STAGE(bufoff, gbase, voff) do { _Pragma("unroll") for (int _i = 0; _i < 2; ++_i) \
;         __builtin_amdgcn_global_load_lds((const unsigned*)((const char*)(gbase) + (voff)[_i]), (LAS unsigned*)(lds + (bufoff) + ldsw + _i * 8192), 16, 0, 0); } while (0)
; #define PG8_LDA(dst, b, h) do { _Pragma("unroll") for (int m = 0; m < 4; ++m) _Pragma("unroll") for (int k = 0; k < 2; ++k) dst[m][k] = *(const LAS bf16x8*)(lds + PG8_SA(b, h) + aoff + m * 2048 + k * 1024); } while (0)
; #define PG8_LDB(dst, b, h) do { _Pragma("unroll") for (int n = 0; n < 2; ++n) _Pragma("unroll") for (int k = 0; k < 2; ++k) dst[n][k] = *(const LAS bf16x8*)(lds + PG8_SB(b, h) + boff + n * 2048 + k * 1024); } while (0)
; #define PG8_MMA(ai, bj, At, Bt) do { __builtin_amdgcn_s_setprio(1); _Pragma("unroll") for (int m = 0; m < 4; ++m) _Pragma("unroll") for (int n = 0; n < 2; ++n) _Pragma("unroll") for (int k = 0; k < 2; ++k) \
;         acc[ai][bj][m][n] = __builtin_amdgcn_mfma_f32_16x16x32_bf16(Bt[n][k], At[m][k], acc[ai][bj][m][n], 0, 0, 0); __builtin_amdgcn_s_setprio(0); } while (0)
; #define PG8_WAIT_V(n) asm volatile("s_waitcnt vmcnt(" #n ")" ::: "memory")
; #define PG8_WAIT_L(n) asm volatile("s_waitcnt lgkmcnt(" #n ")" ::: "memory")
; #define PG8_BAR __builtin_amdgcn_s_barrier()
; #define PG8_SCHED __builtin_amdgcn_sched_barrier(0)
; template <class Epi, class Sched>
; __device__ __forceinline__ void gemm_phase(LAS unsigned char* lds, const int K, const Sched& S, const Epi& E) {
;     ...
;             const bool last = (t == nt - 2);
;             const char* a1 = cA + (size_t)(t + 1) * kstep;
;             const char* a2 = last ? nA : cA + (size_t)(t + 2) * kstep; const char* b2 = last ? nB : cB + (size_t)(t + 2) * kstep;
;             const char* a3 = a2 + kstep; const char* b3 = b2 + kstep;
;             PG8_LDB(B0, 0, 0); PG8_LDB(B1, 0, 1); PG8_SCHED; PG8_LDA(At, 0, 0); PG8_STAGE(PG8_SA(1, 1), a1 + hstep, voffA);
;             PG8_WAIT_V(8); PG8_WAIT_L(0); PG8_BAR; PG8_MMA(0, 0, At, B0); PG8_MMA(0, 1, At, B1); PG8_BAR; PG8_SCHED;
;             PG8_LDA(At, 0, 1); PG8_STAGE(PG8_SB(0, 0), b2, voffB); PG8_STAGE(PG8_SB(0, 1), b2 + hstep, voffB); PG8_STAGE(PG8_SA(0, 0), a2, voffA);
;             PG8_WAIT_V(8); PG8_WAIT_L(0); PG8_BAR; PG8_MMA(1, 0, At, B0); PG8_MMA(1, 1, At, B1); PG8_BAR; PG8_SCHED;
.LBB0_963:
	s_add_u32 s5, s56, 0xfffc0080
	s_addc_u32 s9, s57, -1
	s_add_i32 s10, 0, 0x10000
	s_cmp_eq_u32 s4, 12
	s_cselect_b32 s61, s53, s9
	s_cselect_b32 s60, s52, s5
	v_add_u32_e32 v150, s10, v153
	s_cselect_b32 s59, s55, s2
	s_cselect_b32 s58, s54, s1
	s_add_i32 s5, 0, 0x14000
	ds_read_b128 v[156:159], v150
	ds_read_b128 v[160:163], v150 offset:1024
	ds_read_b128 v[164:167], v150 offset:2048
	ds_read_b128 v[180:183], v150 offset:3072
	v_add_u32_e32 v150, s5, v153
	ds_read_b128 v[184:187], v150
	ds_read_b128 v[188:191], v150 offset:1024
	ds_read_b128 v[192:195], v150 offset:2048
	ds_read_b128 v[196:199], v150 offset:3072
	v_lshl_add_u64 v[150:151], s[56:57], 0, v[146:147]
	s_add_i32 m0, s66, 0xc000
	ds_read_b128 v[200:203], v154
	ds_read_b128 v[204:207], v154 offset:1024
	ds_read_b128 v[208:211], v154 offset:2048
	ds_read_b128 v[212:215], v154 offset:3072
	ds_read_b128 v[216:219], v154 offset:4096
	ds_read_b128 v[220:223], v154 offset:5120
	ds_read_b128 v[224:227], v154 offset:6144
	ds_read_b128 v[228:231], v154 offset:7168
	global_load_lds_dwordx4 v[150:151], off
	v_lshl_add_u64 v[150:151], s[56:57], 0, v[148:149]
	s_add_i32 m0, s66, 0xe000
	s_nop 0
	global_load_lds_dwordx4 v[150:151], off
	s_waitcnt vmcnt(8)
	s_waitcnt lgkmcnt(0)
	s_setprio 1
	s_barrier
	v_mfma_f32_16x16x32_bf16 v[124:127], v[156:159], v[200:203], v[124:127]
	v_mfma_f32_16x16x32_bf16 v[116:119], v[164:167], v[200:203], v[116:119]
	v_mfma_f32_16x16x32_bf16 v[108:111], v[156:159], v[208:211], v[108:111]
	v_mfma_f32_16x16x32_bf16 v[100:103], v[164:167], v[208:211], v[100:103]
	v_mfma_f32_16x16x32_bf16 v[92:95], v[156:159], v[216:219], v[92:95]
	v_mfma_f32_16x16x32_bf16 v[84:87], v[164:167], v[216:219], v[84:87]
	v_mfma_f32_16x16x32_bf16 v[76:79], v[156:159], v[224:227], v[76:79]
	v_mfma_f32_16x16x32_bf16 v[68:71], v[164:167], v[224:227], v[68:71]
	s_setprio 0
	s_setprio 1
	v_mfma_f32_16x16x32_bf16 v[124:127], v[160:163], v[204:207], v[124:127]
	v_mfma_f32_16x16x32_bf16 v[116:119], v[180:183], v[204:207], v[116:119]
	v_mfma_f32_16x16x32_bf16 v[108:111], v[160:163], v[212:215], v[108:111]
	v_mfma_f32_16x16x32_bf16 v[100:103], v[180:183], v[212:215], v[100:103]
	v_mfma_f32_16x16x32_bf16 v[92:95], v[160:163], v[220:223], v[92:95]
	v_mfma_f32_16x16x32_bf16 v[84:87], v[180:183], v[220:223], v[84:87]
	v_mfma_f32_16x16x32_bf16 v[76:79], v[160:163], v[228:231], v[76:79]
	v_mfma_f32_16x16x32_bf16 v[68:71], v[180:183], v[228:231], v[68:71]
	s_setprio 0
	s_setprio 1
	v_mfma_f32_16x16x32_bf16 v[120:123], v[184:187], v[200:203], v[120:123]
	v_mfma_f32_16x16x32_bf16 v[112:115], v[192:195], v[200:203], v[112:115]
	v_mfma_f32_16x16x32_bf16 v[104:107], v[184:187], v[208:211], v[104:107]
	v_mfma_f32_16x16x32_bf16 v[96:99], v[192:195], v[208:211], v[96:99]
	v_mfma_f32_16x16x32_bf16 v[88:91], v[184:187], v[216:219], v[88:91]
	v_mfma_f32_16x16x32_bf16 v[80:83], v[192:195], v[216:219], v[80:83]
	v_mfma_f32_16x16x32_bf16 v[72:75], v[184:187], v[224:227], v[72:75]
	v_mfma_f32_16x16x32_bf16 v[64:67], v[192:195], v[224:227], v[64:67]
	s_setprio 0
	s_setprio 1
	v_mfma_f32_16x16x32_bf16 v[120:123], v[188:191], v[204:207], v[120:123]
	v_mfma_f32_16x16x32_bf16 v[112:115], v[196:199], v[204:207], v[112:115]
	v_mfma_f32_16x16x32_bf16 v[104:107], v[188:191], v[212:215], v[104:107]
	v_mfma_f32_16x16x32_bf16 v[96:99], v[196:199], v[212:215], v[96:99]
	v_mfma_f32_16x16x32_bf16 v[88:91], v[188:191], v[220:223], v[88:91]
	v_mfma_f32_16x16x32_bf16 v[80:83], v[196:199], v[220:223], v[80:83]
	v_mfma_f32_16x16x32_bf16 v[72:75], v[188:191], v[228:231], v[72:75]
	v_mfma_f32_16x16x32_bf16 v[64:67], v[196:199], v[228:231], v[64:67]
	s_barrier
	s_setprio 0
	s_add_i32 s9, s10, s63
	v_lshl_add_u64 v[150:151], s[58:59], 0, v[142:143]
	s_mov_b32 m0, s9
	ds_read_b128 v[200:203], v154 offset:16384
	ds_read_b128 v[204:207], v154 offset:17408
	ds_read_b128 v[208:211], v154 offset:18432
	ds_read_b128 v[212:215], v154 offset:19456
	ds_read_b128 v[216:219], v154 offset:20480
	ds_read_b128 v[220:223], v154 offset:21504
	ds_read_b128 v[224:227], v154 offset:22528
	ds_read_b128 v[228:231], v154 offset:23552
	global_load_lds_dwordx4 v[150:151], off
	s_add_i32 m0, s9, 0x2000
	s_add_u32 s10, s58, 0x40000
	v_lshl_add_u64 v[232:233], s[58:59], 0, v[138:139]
	s_addc_u32 s11, s59, 0
	s_add_i32 s5, s5, s63
	global_load_lds_dwordx4 v[232:233], off
	v_lshl_add_u64 v[234:235], s[10:11], 0, v[142:143]
	s_mov_b32 m0, s5
	v_lshl_add_u64 v[236:237], s[60:61], 0, v[140:141]
	global_load_lds_dwordx4 v[234:235], off
	v_lshl_add_u64 v[234:235], s[10:11], 0, v[138:139]
	s_add_i32 m0, s5, 0x2000
	s_nop 0
	global_load_lds_dwordx4 v[234:235], off
	v_lshl_add_u64 v[234:235], s[60:61], 0, v[144:145]
	s_mov_b32 m0, s66
	s_nop 0
	global_load_lds_dwordx4 v[234:235], off
	s_mov_b32 m0, s67
	s_nop 0
	global_load_lds_dwordx4 v[236:237], off
	s_waitcnt vmcnt(8)
	s_waitcnt lgkmcnt(0)
	s_setprio 1
	s_barrier
; #define PG8_STAGE(bufoff, gbase, voff) do { _Pragma("unroll") for (int _i = 0; _i < 2; ++_i) \
;         __builtin_amdgcn_global_load_lds((const unsigned*)((const char*)(gbase) + (voff)[_i]), (LAS unsigned*)(lds + (bufoff) + ldsw + _i * 8192), 16, 0, 0); } while (0)
; #define PG8_LDA(dst, b, h) do { _Pragma("unroll") for (int m = 0; m < 4; ++m) _Pragma("unroll") for (int k = 0; k < 2; ++k) dst[m][k] = *(const LAS bf16x8*)(lds + PG8_SA(b, h) + aoff + m * 2048 + k * 1024); } while (0)
; #define PG8_LDB(dst, b, h) do { _Pragma("unroll") for (int n = 0; n < 2; ++n) _Pragma("unroll") for (int k = 0; k < 2; ++k) dst[n][k] = *(const LAS bf16x8*)(lds + PG8_SB(b, h) + boff + n * 2048 + k * 1024); } while (0)
; #define PG8_MMA(ai, bj, At, Bt) do { __builtin_amdgcn_s_setprio(1); _Pragma("unroll") for (int m = 0; m < 4; ++m) _Pragma("unroll") for (int n = 0; n < 2; ++n) _Pragma("unroll") for (int k = 0; k < 2; ++k) \
;         acc[ai][bj][m][n] = __builtin_amdgcn_mfma_f32_16x16x32_bf16(Bt[n][k], At[m][k], acc[ai][bj][m][n], 0, 0, 0); __builtin_amdgcn_s_setprio(0); } while (0)
; #define PG8_WAIT_V(n) asm volatile("s_waitcnt vmcnt(" #n ")" ::: "memory")
; #define PG8_WAIT_L(n) asm volatile("s_waitcnt lgkmcnt(" #n ")" ::: "memory")
; #define PG8_BAR __builtin_amdgcn_s_barrier()
; #define PG8_SCHED __builtin_amdgcn_sched_barrier(0)
; template <class Epi, class Sched>
; __device__ __forceinline__ void gemm_phase(LAS unsigned char* lds, const int K, const Sched& S, const Epi& E) {
;     ...
;             PG8_WAIT_V(8); PG8_WAIT_L(0); PG8_BAR; PG8_MMA(1, 0, At, B0); PG8_MMA(1, 1, At, B1); PG8_BAR; PG8_SCHED;
;             PG8_LDB(B0, 1, 0); PG8_LDB(B1, 1, 1); PG8_SCHED; PG8_LDA(At, 1, 0); PG8_STAGE(PG8_SA(0, 1), a2 + hstep, voffA);
;             PG8_WAIT_V(8); PG8_WAIT_L(0); PG8_BAR; PG8_MMA(0, 0, At, B0); PG8_MMA(0, 1, At, B1); PG8_BAR; PG8_SCHED;
	v_mfma_f32_16x16x32_bf16 v[60:63], v[156:159], v[200:203], v[60:63]
	v_mfma_f32_16x16x32_bf16 v[52:55], v[164:167], v[200:203], v[52:55]
	v_mfma_f32_16x16x32_bf16 v[44:47], v[156:159], v[208:211], v[44:47]
	v_mfma_f32_16x16x32_bf16 v[36:39], v[164:167], v[208:211], v[36:39]
	v_mfma_f32_16x16x32_bf16 v[28:31], v[156:159], v[216:219], v[28:31]
	v_mfma_f32_16x16x32_bf16 v[20:23], v[164:167], v[216:219], v[20:23]
	v_mfma_f32_16x16x32_bf16 v[12:15], v[156:159], v[224:227], v[12:15]
	v_mfma_f32_16x16x32_bf16 v[4:7], v[164:167], v[224:227], v[4:7]
	s_setprio 0
	s_setprio 1
	v_mfma_f32_16x16x32_bf16 v[60:63], v[160:163], v[204:207], v[60:63]
	v_mfma_f32_16x16x32_bf16 v[52:55], v[180:183], v[204:207], v[52:55]
	v_mfma_f32_16x16x32_bf16 v[44:47], v[160:163], v[212:215], v[44:47]
	v_mfma_f32_16x16x32_bf16 v[36:39], v[180:183], v[212:215], v[36:39]
	v_mfma_f32_16x16x32_bf16 v[28:31], v[160:163], v[220:223], v[28:31]
	v_mfma_f32_16x16x32_bf16 v[20:23], v[180:183], v[220:223], v[20:23]
	v_mfma_f32_16x16x32_bf16 v[12:15], v[160:163], v[228:231], v[12:15]
	v_mfma_f32_16x16x32_bf16 v[4:7], v[180:183], v[228:231], v[4:7]
	s_setprio 0
	s_setprio 1
	v_mfma_f32_16x16x32_bf16 v[56:59], v[184:187], v[200:203], v[56:59]
	v_mfma_f32_16x16x32_bf16 v[48:51], v[192:195], v[200:203], v[48:51]
	v_mfma_f32_16x16x32_bf16 v[40:43], v[184:187], v[208:211], v[40:43]
	v_mfma_f32_16x16x32_bf16 v[32:35], v[192:195], v[208:211], v[32:35]
	v_mfma_f32_16x16x32_bf16 v[24:27], v[184:187], v[216:219], v[24:27]
	v_mfma_f32_16x16x32_bf16 v[16:19], v[192:195], v[216:219], v[16:19]
	v_mfma_f32_16x16x32_bf16 v[8:11], v[184:187], v[224:227], v[8:11]
	v_mfma_f32_16x16x32_bf16 v[0:3], v[192:195], v[224:227], v[0:3]
	s_setprio 0
	s_setprio 1
	v_mfma_f32_16x16x32_bf16 v[56:59], v[188:191], v[204:207], v[56:59]
	v_mfma_f32_16x16x32_bf16 v[48:51], v[196:199], v[204:207], v[48:51]
	v_mfma_f32_16x16x32_bf16 v[40:43], v[188:191], v[212:215], v[40:43]
	v_mfma_f32_16x16x32_bf16 v[32:35], v[196:199], v[212:215], v[32:35]
	v_mfma_f32_16x16x32_bf16 v[24:27], v[188:191], v[220:223], v[24:27]
	v_mfma_f32_16x16x32_bf16 v[16:19], v[196:199], v[220:223], v[16:19]
	v_mfma_f32_16x16x32_bf16 v[8:11], v[188:191], v[228:231], v[8:11]
	v_mfma_f32_16x16x32_bf16 v[0:3], v[196:199], v[228:231], v[0:3]
	s_barrier
	s_setprio 0
	s_add_i32 s5, 0, 0x18000
	v_add_u32_e32 v155, s5, v153
	s_add_i32 s9, 0, 0x1c000
	ds_read_b128 v[156:159], v155
	ds_read_b128 v[160:163], v155 offset:1024
	ds_read_b128 v[164:167], v155 offset:2048
	ds_read_b128 v[180:183], v155 offset:3072
	v_add_u32_e32 v155, s9, v153
	ds_read_b128 v[184:187], v155
	ds_read_b128 v[188:191], v155 offset:1024
	ds_read_b128 v[192:195], v155 offset:2048
	ds_read_b128 v[196:199], v155 offset:3072
	s_add_u32 s10, s60, 0x40000
	s_addc_u32 s11, s61, 0
	s_mov_b32 m0, s68
	v_lshl_add_u64 v[238:239], s[10:11], 0, v[144:145]
	ds_read_b128 v[200:203], v154 offset:32768
	ds_read_b128 v[204:207], v154 offset:33792
	ds_read_b128 v[208:211], v154 offset:34816
	ds_read_b128 v[212:215], v154 offset:35840
	ds_read_b128 v[216:219], v154 offset:36864
	ds_read_b128 v[220:223], v154 offset:37888
	ds_read_b128 v[224:227], v154 offset:38912
	ds_read_b128 v[228:231], v154 offset:39936
	global_load_lds_dwordx4 v[238:239], off
	v_lshl_add_u64 v[238:239], s[10:11], 0, v[140:141]
	s_mov_b32 m0, s69
	s_nop 0
	global_load_lds_dwordx4 v[238:239], off
	s_waitcnt vmcnt(8)
	s_waitcnt lgkmcnt(0)
	s_setprio 1
	s_barrier
	v_mfma_f32_16x16x32_bf16 v[124:127], v[156:159], v[200:203], v[124:127]
	v_mfma_f32_16x16x32_bf16 v[116:119], v[164:167], v[200:203], v[116:119]
	v_mfma_f32_16x16x32_bf16 v[108:111], v[156:159], v[208:211], v[108:111]
	v_mfma_f32_16x16x32_bf16 v[100:103], v[164:167], v[208:211], v[100:103]
	v_mfma_f32_16x16x32_bf16 v[92:95], v[156:159], v[216:219], v[92:95]
	v_mfma_f32_16x16x32_bf16 v[84:87], v[164:167], v[216:219], v[84:87]
	v_mfma_f32_16x16x32_bf16 v[76:79], v[156:159], v[224:227], v[76:79]
	v_mfma_f32_16x16x32_bf16 v[68:71], v[164:167], v[224:227], v[68:71]
	s_setprio 0
	s_setprio 1
	v_mfma_f32_16x16x32_bf16 v[124:127], v[160:163], v[204:207], v[124:127]
	v_mfma_f32_16x16x32_bf16 v[116:119], v[180:183], v[204:207], v[116:119]
	v_mfma_f32_16x16x32_bf16 v[108:111], v[160:163], v[212:215], v[108:111]
	v_mfma_f32_16x16x32_bf16 v[100:103], v[180:183], v[212:215], v[100:103]
	v_mfma_f32_16x16x32_bf16 v[92:95], v[160:163], v[220:223], v[92:95]
	v_mfma_f32_16x16x32_bf16 v[84:87], v[180:183], v[220:223], v[84:87]
	v_mfma_f32_16x16x32_bf16 v[76:79], v[160:163], v[228:231], v[76:79]
	v_mfma_f32_16x16x32_bf16 v[68:71], v[180:183], v[228:231], v[68:71]
	s_setprio 0
	s_setprio 1
	v_mfma_f32_16x16x32_bf16 v[120:123], v[184:187], v[200:203], v[120:123]
	v_mfma_f32_16x16x32_bf16 v[112:115], v[192:195], v[200:203], v[112:115]
	v_mfma_f32_16x16x32_bf16 v[104:107], v[184:187], v[208:211], v[104:107]
	v_mfma_f32_16x16x32_bf16 v[96:99], v[192:195], v[208:211], v[96:99]
	v_mfma_f32_16x16x32_bf16 v[88:91], v[184:187], v[216:219], v[88:91]
	v_mfma_f32_16x16x32_bf16 v[80:83], v[192:195], v[216:219], v[80:83]
	v_mfma_f32_16x16x32_bf16 v[72:75], v[184:187], v[224:227], v[72:75]
	v_mfma_f32_16x16x32_bf16 v[64:67], v[192:195], v[224:227], v[64:67]
	s_setprio 0
	s_setprio 1
	v_mfma_f32_16x16x32_bf16 v[120:123], v[188:191], v[204:207], v[120:123]
	v_mfma_f32_16x16x32_bf16 v[112:115], v[196:199], v[204:207], v[112:115]
	v_mfma_f32_16x16x32_bf16 v[104:107], v[188:191], v[212:215], v[104:107]
	v_mfma_f32_16x16x32_bf16 v[96:99], v[196:199], v[212:215], v[96:99]
	v_mfma_f32_16x16x32_bf16 v[88:91], v[188:191], v[220:223], v[88:91]
	v_mfma_f32_16x16x32_bf16 v[80:83], v[196:199], v[220:223], v[80:83]
	v_mfma_f32_16x16x32_bf16 v[72:75], v[188:191], v[228:231], v[72:75]
	v_mfma_f32_16x16x32_bf16 v[64:67], v[196:199], v[228:231], v[64:67]
	s_barrier
; #define PG8_STAGE(bufoff, gbase, voff) do { _Pragma("unroll") for (int _i = 0; _i < 2; ++_i) \
;         __builtin_amdgcn_global_load_lds((const unsigned*)((const char*)(gbase) + (voff)[_i]), (LAS unsigned*)(lds + (bufoff) + ldsw + _i * 8192), 16, 0, 0); } while (0)
; #define PG8_LDA(dst, b, h) do { _Pragma("unroll") for (int m = 0; m < 4; ++m) _Pragma("unroll") for (int k = 0; k < 2; ++k) dst[m][k] = *(const LAS bf16x8*)(lds + PG8_SA(b, h) + aoff + m * 2048 + k * 1024); } while (0)
; #define PG8_MMA(ai, bj, At, Bt) do { __builtin_amdgcn_s_setprio(1); _Pragma("unroll") for (int m = 0; m < 4; ++m) _Pragma("unroll") for (int n = 0; n < 2; ++n) _Pragma("unroll") for (int k = 0; k < 2; ++k) \
;         acc[ai][bj][m][n] = __builtin_amdgcn_mfma_f32_16x16x32_bf16(Bt[n][k], At[m][k], acc[ai][bj][m][n], 0, 0, 0); __builtin_amdgcn_s_setprio(0); } while (0)
; #define PG8_WAIT_V(n) asm volatile("s_waitcnt vmcnt(" #n ")" ::: "memory")
; #define PG8_WAIT_L(n) asm volatile("s_waitcnt lgkmcnt(" #n ")" ::: "memory")
; #define PG8_BAR __builtin_amdgcn_s_barrier()
; #define PG8_SCHED __builtin_amdgcn_sched_barrier(0)
; template <class Epi, class Sched>
; __device__ __forceinline__ void gemm_phase(LAS unsigned char* lds, const int K, const Sched& S, const Epi& E) {
;     ...
;             PG8_LDA(At, 1, 1); PG8_STAGE(PG8_SB(1, 0), b3, voffB); PG8_STAGE(PG8_SB(1, 1), b3 + hstep, voffB); PG8_STAGE(PG8_SA(1, 0), a3, voffA);
;             PG8_WAIT_V(8); PG8_WAIT_L(0); PG8_BAR; PG8_MMA(1, 0, At, B0); PG8_MMA(1, 1, At, B1); PG8_BAR; PG8_SCHED;
;         }
;         if (wr == 0) PG8_BAR;
	s_setprio 0
	s_add_i32 s5, s5, s63
	v_lshl_add_u64 v[150:151], v[150:151], 0, s[36:37]
	s_mov_b32 m0, s5
	ds_read_b128 v[200:203], v154 offset:49152
	ds_read_b128 v[204:207], v154 offset:50176
	ds_read_b128 v[208:211], v154 offset:51200
	ds_read_b128 v[212:215], v154 offset:52224
	ds_read_b128 v[216:219], v154 offset:53248
	ds_read_b128 v[220:223], v154 offset:54272
	ds_read_b128 v[224:227], v154 offset:55296
	ds_read_b128 v[228:231], v154 offset:56320
	global_load_lds_dwordx4 v[150:151], off
	s_add_i32 m0, s5, 0x2000
	s_add_u32 s10, s58, 0x40080
	v_lshl_add_u64 v[150:151], v[232:233], 0, s[36:37]
	s_addc_u32 s11, s59, 0
	s_add_i32 s5, s9, s63
	global_load_lds_dwordx4 v[150:151], off
	v_lshl_add_u64 v[150:151], s[10:11], 0, v[142:143]
	s_mov_b32 m0, s5
	s_nop 0
	global_load_lds_dwordx4 v[150:151], off
	v_lshl_add_u64 v[150:151], s[10:11], 0, v[138:139]
	s_add_i32 m0, s5, 0x2000
	s_nop 0
	global_load_lds_dwordx4 v[150:151], off
	v_lshl_add_u64 v[150:151], v[234:235], 0, s[36:37]
	s_mov_b32 m0, s70
	s_nop 0
	global_load_lds_dwordx4 v[150:151], off
	v_lshl_add_u64 v[150:151], v[236:237], 0, s[36:37]
	s_mov_b32 m0, s71
	s_nop 0
	global_load_lds_dwordx4 v[150:151], off
	s_waitcnt vmcnt(8)
	s_waitcnt lgkmcnt(0)
	s_setprio 1
	s_barrier
	v_mfma_f32_16x16x32_bf16 v[60:63], v[156:159], v[200:203], v[60:63]
	v_mfma_f32_16x16x32_bf16 v[52:55], v[164:167], v[200:203], v[52:55]
	v_mfma_f32_16x16x32_bf16 v[44:47], v[156:159], v[208:211], v[44:47]
	v_mfma_f32_16x16x32_bf16 v[36:39], v[164:167], v[208:211], v[36:39]
	v_mfma_f32_16x16x32_bf16 v[28:31], v[156:159], v[216:219], v[28:31]
	v_mfma_f32_16x16x32_bf16 v[20:23], v[164:167], v[216:219], v[20:23]
	v_mfma_f32_16x16x32_bf16 v[12:15], v[156:159], v[224:227], v[12:15]
	v_mfma_f32_16x16x32_bf16 v[4:7], v[164:167], v[224:227], v[4:7]
	s_setprio 0
	s_setprio 1
	v_mfma_f32_16x16x32_bf16 v[60:63], v[160:163], v[204:207], v[60:63]
	v_mfma_f32_16x16x32_bf16 v[52:55], v[180:183], v[204:207], v[52:55]
	v_mfma_f32_16x16x32_bf16 v[44:47], v[160:163], v[212:215], v[44:47]
	v_mfma_f32_16x16x32_bf16 v[36:39], v[180:183], v[212:215], v[36:39]
	v_mfma_f32_16x16x32_bf16 v[28:31], v[160:163], v[220:223], v[28:31]
	v_mfma_f32_16x16x32_bf16 v[20:23], v[180:183], v[220:223], v[20:23]
	v_mfma_f32_16x16x32_bf16 v[12:15], v[160:163], v[228:231], v[12:15]
	v_mfma_f32_16x16x32_bf16 v[4:7], v[180:183], v[228:231], v[4:7]
	s_setprio 0
	s_setprio 1
	v_mfma_f32_16x16x32_bf16 v[56:59], v[184:187], v[200:203], v[56:59]
	v_mfma_f32_16x16x32_bf16 v[48:51], v[192:195], v[200:203], v[48:51]
	v_mfma_f32_16x16x32_bf16 v[40:43], v[184:187], v[208:211], v[40:43]
	v_mfma_f32_16x16x32_bf16 v[32:35], v[192:195], v[208:211], v[32:35]
	v_mfma_f32_16x16x32_bf16 v[24:27], v[184:187], v[216:219], v[24:27]
	v_mfma_f32_16x16x32_bf16 v[16:19], v[192:195], v[216:219], v[16:19]
	v_mfma_f32_16x16x32_bf16 v[8:11], v[184:187], v[224:227], v[8:11]
	v_mfma_f32_16x16x32_bf16 v[0:3], v[192:195], v[224:227], v[0:3]
	s_setprio 0
	s_setprio 1
	v_mfma_f32_16x16x32_bf16 v[56:59], v[188:191], v[204:207], v[56:59]
	v_mfma_f32_16x16x32_bf16 v[48:51], v[196:199], v[204:207], v[48:51]
	v_mfma_f32_16x16x32_bf16 v[40:43], v[188:191], v[212:215], v[40:43]
	v_mfma_f32_16x16x32_bf16 v[32:35], v[196:199], v[212:215], v[32:35]
	v_mfma_f32_16x16x32_bf16 v[24:27], v[188:191], v[220:223], v[24:27]
	v_mfma_f32_16x16x32_bf16 v[16:19], v[196:199], v[220:223], v[16:19]
	v_mfma_f32_16x16x32_bf16 v[8:11], v[188:191], v[228:231], v[8:11]
	v_mfma_f32_16x16x32_bf16 v[0:3], v[196:199], v[228:231], v[0:3]
	s_barrier
	s_setprio 0
	s_add_i32 s4, s4, 2
	s_add_u32 s56, s56, 0x100
	s_addc_u32 s57, s57, 0
	s_add_u32 s1, s1, 0x100
	s_addc_u32 s2, s2, 0
	s_cmp_gt_u32 s4, 13
	s_cbranch_scc0 .LBB0_963
	s_and_b64 vcc, exec, s[46:47]
	s_cbranch_vccz .LBB0_966
	s_barrier

; #define PG8_STAGE(bufoff, gbase, voff) do { _Pragma("unroll") for (int _i = 0; _i < 2; ++_i) \
;         __builtin_amdgcn_global_load_lds((const unsigned*)((const char*)(gbase) + (voff)[_i]), (LAS unsigned*)(lds + (bufoff) + ldsw + _i * 8192), 16, 0, 0); } while (0)
; #define PG8_LDA(dst, b, h) do { _Pragma("unroll") for (int m = 0; m < 4; ++m) _Pragma("unroll") for (int k = 0; k < 2; ++k) dst[m][k] = *(const LAS bf16x8*)(lds + PG8_SA(b, h) + aoff + m * 2048 + k * 1024); } while (0)
; #define PG8_LDB(dst, b, h) do { _Pragma("unroll") for (int n = 0; n < 2; ++n) _Pragma("unroll") for (int k = 0; k < 2; ++k) dst[n][k] = *(const LAS bf16x8*)(lds + PG8_SB(b, h) + boff + n * 2048 + k * 1024); } while (0)
; #define PG8_MMA(ai, bj, At, Bt) do { __builtin_amdgcn_s_setprio(1); _Pragma("unroll") for (int m = 0; m < 4; ++m) _Pragma("unroll") for (int n = 0; n < 2; ++n) _Pragma("unroll") for (int k = 0; k < 2; ++k) \
;         acc[ai][bj][m][n] = __builtin_amdgcn_mfma_f32_16x16x32_bf16(Bt[n][k], At[m][k], acc[ai][bj][m][n], 0, 0, 0); __builtin_amdgcn_s_setprio(0); } while (0)
; #define PG8_WAIT_V(n) asm volatile("s_waitcnt vmcnt(" #n ")" ::: "memory")
; #define PG8_WAIT_L(n) asm volatile("s_waitcnt lgkmcnt(" #n ")" ::: "memory")
; #define PG8_BAR __builtin_amdgcn_s_barrier()
; #define PG8_SCHED __builtin_amdgcn_sched_barrier(0)
; template <class Epi, class Sched>
; __device__ __forceinline__ void gemm_phase(LAS unsigned char* lds, const int K, const Sched& S, const Epi& E) {
;     ...
;             const bool last = (t == nt - 2);
;             const char* a1 = cA + (size_t)(t + 1) * kstep;
;             const char* a2 = last ? nA : cA + (size_t)(t + 2) * kstep; const char* b2 = last ? nB : cB + (size_t)(t + 2) * kstep;
;             const char* a3 = a2 + kstep; const char* b3 = b2 + kstep;
;             PG8_LDB(B0, 0, 0); PG8_LDB(B1, 0, 1); PG8_SCHED; PG8_LDA(At, 0, 0); PG8_STAGE(PG8_SA(1, 1), a1 + hstep, voffA);
;             PG8_WAIT_V(8); PG8_WAIT_L(0); PG8_BAR; PG8_MMA(0, 0, At, B0); PG8_MMA(0, 1, At, B1); PG8_BAR; PG8_SCHED;
;             PG8_LDA(At, 0, 1); PG8_STAGE(PG8_SB(0, 0), b2, voffB); PG8_STAGE(PG8_SB(0, 1), b2 + hstep, voffB); PG8_STAGE(PG8_SA(0, 0), a2, voffA);
;             PG8_WAIT_V(8); PG8_WAIT_L(0); PG8_BAR; PG8_MMA(1, 0, At, B0); PG8_MMA(1, 1, At, B1); PG8_BAR; PG8_SCHED;
.LBB0_1073:
	s_add_i32 s13, s12, 2
	s_add_u32 s52, s8, 0x100
	s_addc_u32 s53, s9, 0
	s_add_i32 s14, 0, 0x10000
	s_cmp_eq_u32 s5, s12
	s_cselect_b32 s57, s0, s53
	s_cselect_b32 s56, s1, s52
	s_cselect_b32 s55, s2, s11
	s_cselect_b32 s54, s4, s10
	s_add_i32 s12, 0, 0x14000
	v_add_u32_e32 v158, s14, v164
	v_add_u32_e32 v162, s12, v164
	ds_read_b128 v[146:149], v158
	ds_read_b128 v[150:153], v158 offset:1024
	ds_read_b128 v[154:157], v158 offset:2048
	ds_read_b128 v[158:161], v158 offset:3072
	ds_read_b128 v[180:183], v162
	ds_read_b128 v[184:187], v162 offset:1024
	ds_read_b128 v[188:191], v162 offset:2048
	ds_read_b128 v[192:195], v162 offset:3072
	v_lshl_add_u64 v[162:163], s[8:9], 0, v[142:143]
	s_add_i32 m0, s61, 0xc000
	ds_read_b128 v[196:199], v166
	ds_read_b128 v[200:203], v166 offset:1024
	ds_read_b128 v[204:207], v166 offset:2048
	ds_read_b128 v[208:211], v166 offset:3072
	ds_read_b128 v[212:215], v166 offset:4096
	ds_read_b128 v[216:219], v166 offset:5120
	ds_read_b128 v[220:223], v166 offset:6144
	ds_read_b128 v[224:227], v166 offset:7168
	global_load_lds_dwordx4 v[162:163], off
	v_lshl_add_u64 v[162:163], s[8:9], 0, v[144:145]
	s_add_i32 m0, s61, 0xe000
	s_nop 0
	global_load_lds_dwordx4 v[162:163], off
	s_waitcnt vmcnt(8)
	s_waitcnt lgkmcnt(0)
	s_setprio 1
	s_barrier
	v_mfma_f32_16x16x32_bf16 v[124:127], v[146:149], v[196:199], v[124:127]
	v_mfma_f32_16x16x32_bf16 v[92:95], v[154:157], v[196:199], v[92:95]
	v_mfma_f32_16x16x32_bf16 v[120:123], v[146:149], v[204:207], v[120:123]
	v_mfma_f32_16x16x32_bf16 v[88:91], v[154:157], v[204:207], v[88:91]
	v_mfma_f32_16x16x32_bf16 v[116:119], v[146:149], v[212:215], v[116:119]
	v_mfma_f32_16x16x32_bf16 v[84:87], v[154:157], v[212:215], v[84:87]
	v_mfma_f32_16x16x32_bf16 v[112:115], v[146:149], v[220:223], v[112:115]
	v_mfma_f32_16x16x32_bf16 v[80:83], v[154:157], v[220:223], v[80:83]
	s_setprio 0
	s_setprio 1
	v_mfma_f32_16x16x32_bf16 v[124:127], v[150:153], v[200:203], v[124:127]
	v_mfma_f32_16x16x32_bf16 v[92:95], v[158:161], v[200:203], v[92:95]
	v_mfma_f32_16x16x32_bf16 v[120:123], v[150:153], v[208:211], v[120:123]
	v_mfma_f32_16x16x32_bf16 v[88:91], v[158:161], v[208:211], v[88:91]
	v_mfma_f32_16x16x32_bf16 v[116:119], v[150:153], v[216:219], v[116:119]
	v_mfma_f32_16x16x32_bf16 v[84:87], v[158:161], v[216:219], v[84:87]
	v_mfma_f32_16x16x32_bf16 v[112:115], v[150:153], v[224:227], v[112:115]
	v_mfma_f32_16x16x32_bf16 v[80:83], v[158:161], v[224:227], v[80:83]
	s_setprio 0
	s_setprio 1
	v_mfma_f32_16x16x32_bf16 v[60:63], v[180:183], v[196:199], v[60:63]
	v_mfma_f32_16x16x32_bf16 v[28:31], v[188:191], v[196:199], v[28:31]
	v_mfma_f32_16x16x32_bf16 v[56:59], v[180:183], v[204:207], v[56:59]
	v_mfma_f32_16x16x32_bf16 v[24:27], v[188:191], v[204:207], v[24:27]
	v_mfma_f32_16x16x32_bf16 v[52:55], v[180:183], v[212:215], v[52:55]
	v_mfma_f32_16x16x32_bf16 v[20:23], v[188:191], v[212:215], v[20:23]
	v_mfma_f32_16x16x32_bf16 v[48:51], v[180:183], v[220:223], v[48:51]
	v_mfma_f32_16x16x32_bf16 v[16:19], v[188:191], v[220:223], v[16:19]
	s_setprio 0
	s_setprio 1
	v_mfma_f32_16x16x32_bf16 v[60:63], v[184:187], v[200:203], v[60:63]
	v_mfma_f32_16x16x32_bf16 v[28:31], v[192:195], v[200:203], v[28:31]
	v_mfma_f32_16x16x32_bf16 v[56:59], v[184:187], v[208:211], v[56:59]
	v_mfma_f32_16x16x32_bf16 v[24:27], v[192:195], v[208:211], v[24:27]
	v_mfma_f32_16x16x32_bf16 v[52:55], v[184:187], v[216:219], v[52:55]
	v_mfma_f32_16x16x32_bf16 v[20:23], v[192:195], v[216:219], v[20:23]
	v_mfma_f32_16x16x32_bf16 v[48:51], v[184:187], v[224:227], v[48:51]
	v_mfma_f32_16x16x32_bf16 v[16:19], v[192:195], v[224:227], v[16:19]
	s_barrier
	s_setprio 0
	s_add_i32 s8, s14, s60
	v_lshl_add_u64 v[162:163], s[54:55], 0, v[128:129]
	s_mov_b32 m0, s8
	ds_read_b128 v[196:199], v166 offset:16384
	ds_read_b128 v[200:203], v166 offset:17408
	ds_read_b128 v[204:207], v166 offset:18432
	ds_read_b128 v[208:211], v166 offset:19456
	ds_read_b128 v[212:215], v166 offset:20480
	ds_read_b128 v[216:219], v166 offset:21504
	ds_read_b128 v[220:223], v166 offset:22528
	ds_read_b128 v[224:227], v166 offset:23552
	global_load_lds_dwordx4 v[162:163], off
	s_add_i32 m0, s8, 0x2000
	s_add_u32 s8, s54, 0xb0000
	v_lshl_add_u64 v[228:229], s[54:55], 0, v[138:139]
	s_addc_u32 s9, s55, 0
	s_add_i32 s12, s12, s60
	global_load_lds_dwordx4 v[228:229], off
	v_lshl_add_u64 v[230:231], s[8:9], 0, v[128:129]
	s_mov_b32 m0, s12
	v_lshl_add_u64 v[232:233], s[56:57], 0, v[138:139]
	global_load_lds_dwordx4 v[230:231], off
	v_lshl_add_u64 v[230:231], s[8:9], 0, v[138:139]
	s_add_i32 m0, s12, 0x2000
	s_nop 0
	global_load_lds_dwordx4 v[230:231], off
	v_lshl_add_u64 v[230:231], s[56:57], 0, v[128:129]
	s_mov_b32 m0, s61
	s_nop 0
	global_load_lds_dwordx4 v[230:231], off
	s_mov_b32 m0, s63
	s_nop 0
	global_load_lds_dwordx4 v[232:233], off
	s_waitcnt vmcnt(8)
	s_waitcnt lgkmcnt(0)
	s_setprio 1
	s_barrier
; #define PG8_STAGE(bufoff, gbase, voff) do { _Pragma("unroll") for (int _i = 0; _i < 2; ++_i) \
;         __builtin_amdgcn_global_load_lds((const unsigned*)((const char*)(gbase) + (voff)[_i]), (LAS unsigned*)(lds + (bufoff) + ldsw + _i * 8192), 16, 0, 0); } while (0)
; #define PG8_LDA(dst, b, h) do { _Pragma("unroll") for (int m = 0; m < 4; ++m) _Pragma("unroll") for (int k = 0; k < 2; ++k) dst[m][k] = *(const LAS bf16x8*)(lds + PG8_SA(b, h) + aoff + m * 2048 + k * 1024); } while (0)
; #define PG8_LDB(dst, b, h) do { _Pragma("unroll") for (int n = 0; n < 2; ++n) _Pragma("unroll") for (int k = 0; k < 2; ++k) dst[n][k] = *(const LAS bf16x8*)(lds + PG8_SB(b, h) + boff + n * 2048 + k * 1024); } while (0)
; #define PG8_MMA(ai, bj, At, Bt) do { __builtin_amdgcn_s_setprio(1); _Pragma("unroll") for (int m = 0; m < 4; ++m) _Pragma("unroll") for (int n = 0; n < 2; ++n) _Pragma("unroll") for (int k = 0; k < 2; ++k) \
;         acc[ai][bj][m][n] = __builtin_amdgcn_mfma_f32_16x16x32_bf16(Bt[n][k], At[m][k], acc[ai][bj][m][n], 0, 0, 0); __builtin_amdgcn_s_setprio(0); } while (0)
; #define PG8_WAIT_V(n) asm volatile("s_waitcnt vmcnt(" #n ")" ::: "memory")
; #define PG8_WAIT_L(n) asm volatile("s_waitcnt lgkmcnt(" #n ")" ::: "memory")
; #define PG8_BAR __builtin_amdgcn_s_barrier()
; #define PG8_SCHED __builtin_amdgcn_sched_barrier(0)
; template <class Epi, class Sched>
; __device__ __forceinline__ void gemm_phase(LAS unsigned char* lds, const int K, const Sched& S, const Epi& E) {
;     ...
;             PG8_WAIT_V(8); PG8_WAIT_L(0); PG8_BAR; PG8_MMA(1, 0, At, B0); PG8_MMA(1, 1, At, B1); PG8_BAR; PG8_SCHED;
;             PG8_LDB(B0, 1, 0); PG8_LDB(B1, 1, 1); PG8_SCHED; PG8_LDA(At, 1, 0); PG8_STAGE(PG8_SA(0, 1), a2 + hstep, voffA);
;             PG8_WAIT_V(8); PG8_WAIT_L(0); PG8_BAR; PG8_MMA(0, 0, At, B0); PG8_MMA(0, 1, At, B1); PG8_BAR; PG8_SCHED;
	v_mfma_f32_16x16x32_bf16 v[108:111], v[146:149], v[196:199], v[108:111]
	v_mfma_f32_16x16x32_bf16 v[76:79], v[154:157], v[196:199], v[76:79]
	v_mfma_f32_16x16x32_bf16 v[104:107], v[146:149], v[204:207], v[104:107]
	v_mfma_f32_16x16x32_bf16 v[72:75], v[154:157], v[204:207], v[72:75]
	v_mfma_f32_16x16x32_bf16 v[100:103], v[146:149], v[212:215], v[100:103]
	v_mfma_f32_16x16x32_bf16 v[68:71], v[154:157], v[212:215], v[68:71]
	v_mfma_f32_16x16x32_bf16 v[96:99], v[146:149], v[220:223], v[96:99]
	v_mfma_f32_16x16x32_bf16 v[64:67], v[154:157], v[220:223], v[64:67]
	s_setprio 0
	s_setprio 1
	v_mfma_f32_16x16x32_bf16 v[108:111], v[150:153], v[200:203], v[108:111]
	v_mfma_f32_16x16x32_bf16 v[76:79], v[158:161], v[200:203], v[76:79]
	v_mfma_f32_16x16x32_bf16 v[104:107], v[150:153], v[208:211], v[104:107]
	v_mfma_f32_16x16x32_bf16 v[72:75], v[158:161], v[208:211], v[72:75]
	v_mfma_f32_16x16x32_bf16 v[100:103], v[150:153], v[216:219], v[100:103]
	v_mfma_f32_16x16x32_bf16 v[68:71], v[158:161], v[216:219], v[68:71]
	v_mfma_f32_16x16x32_bf16 v[96:99], v[150:153], v[224:227], v[96:99]
	v_mfma_f32_16x16x32_bf16 v[64:67], v[158:161], v[224:227], v[64:67]
	s_setprio 0
	s_setprio 1
	v_mfma_f32_16x16x32_bf16 v[44:47], v[180:183], v[196:199], v[44:47]
	v_mfma_f32_16x16x32_bf16 v[12:15], v[188:191], v[196:199], v[12:15]
	v_mfma_f32_16x16x32_bf16 v[40:43], v[180:183], v[204:207], v[40:43]
	v_mfma_f32_16x16x32_bf16 v[8:11], v[188:191], v[204:207], v[8:11]
	v_mfma_f32_16x16x32_bf16 v[36:39], v[180:183], v[212:215], v[36:39]
	v_mfma_f32_16x16x32_bf16 v[4:7], v[188:191], v[212:215], v[4:7]
	v_mfma_f32_16x16x32_bf16 v[32:35], v[180:183], v[220:223], v[32:35]
	v_mfma_f32_16x16x32_bf16 v[0:3], v[188:191], v[220:223], v[0:3]
	s_setprio 0
	s_setprio 1
	v_mfma_f32_16x16x32_bf16 v[44:47], v[184:187], v[200:203], v[44:47]
	v_mfma_f32_16x16x32_bf16 v[12:15], v[192:195], v[200:203], v[12:15]
	v_mfma_f32_16x16x32_bf16 v[40:43], v[184:187], v[208:211], v[40:43]
	v_mfma_f32_16x16x32_bf16 v[8:11], v[192:195], v[208:211], v[8:11]
	v_mfma_f32_16x16x32_bf16 v[36:39], v[184:187], v[216:219], v[36:39]
	v_mfma_f32_16x16x32_bf16 v[4:7], v[192:195], v[216:219], v[4:7]
	v_mfma_f32_16x16x32_bf16 v[32:35], v[184:187], v[224:227], v[32:35]
	v_mfma_f32_16x16x32_bf16 v[0:3], v[192:195], v[224:227], v[0:3]
	s_barrier
	s_setprio 0
	s_add_i32 s12, 0, 0x18000
	s_add_i32 s14, 0, 0x1c000
	v_add_u32_e32 v158, s12, v164
	v_add_u32_e32 v167, s14, v164
	ds_read_b128 v[146:149], v158
	ds_read_b128 v[150:153], v158 offset:1024
	ds_read_b128 v[154:157], v158 offset:2048
	ds_read_b128 v[158:161], v158 offset:3072
	ds_read_b128 v[180:183], v167
	ds_read_b128 v[184:187], v167 offset:1024
	ds_read_b128 v[188:191], v167 offset:2048
	ds_read_b128 v[192:195], v167 offset:3072
	s_add_u32 s8, s56, 0xb0000
	s_addc_u32 s9, s57, 0
	s_mov_b32 m0, s64
	v_lshl_add_u64 v[234:235], s[8:9], 0, v[128:129]
	ds_read_b128 v[196:199], v166 offset:32768
	ds_read_b128 v[200:203], v166 offset:33792
	ds_read_b128 v[204:207], v166 offset:34816
	ds_read_b128 v[208:211], v166 offset:35840
	ds_read_b128 v[212:215], v166 offset:36864
	ds_read_b128 v[216:219], v166 offset:37888
	ds_read_b128 v[220:223], v166 offset:38912
	ds_read_b128 v[224:227], v166 offset:39936
	global_load_lds_dwordx4 v[234:235], off
	v_lshl_add_u64 v[234:235], s[8:9], 0, v[138:139]
	s_mov_b32 m0, s65
	s_nop 0
	global_load_lds_dwordx4 v[234:235], off
	s_waitcnt vmcnt(8)
	s_waitcnt lgkmcnt(0)
	s_setprio 1
	s_barrier
	v_mfma_f32_16x16x32_bf16 v[124:127], v[146:149], v[196:199], v[124:127]
	v_mfma_f32_16x16x32_bf16 v[92:95], v[154:157], v[196:199], v[92:95]
	v_mfma_f32_16x16x32_bf16 v[120:123], v[146:149], v[204:207], v[120:123]
	v_mfma_f32_16x16x32_bf16 v[88:91], v[154:157], v[204:207], v[88:91]
	v_mfma_f32_16x16x32_bf16 v[116:119], v[146:149], v[212:215], v[116:119]
	v_mfma_f32_16x16x32_bf16 v[84:87], v[154:157], v[212:215], v[84:87]
	v_mfma_f32_16x16x32_bf16 v[112:115], v[146:149], v[220:223], v[112:115]
	v_mfma_f32_16x16x32_bf16 v[80:83], v[154:157], v[220:223], v[80:83]
	s_setprio 0
	s_setprio 1
	v_mfma_f32_16x16x32_bf16 v[124:127], v[150:153], v[200:203], v[124:127]
	v_mfma_f32_16x16x32_bf16 v[92:95], v[158:161], v[200:203], v[92:95]
	v_mfma_f32_16x16x32_bf16 v[120:123], v[150:153], v[208:211], v[120:123]
	v_mfma_f32_16x16x32_bf16 v[88:91], v[158:161], v[208:211], v[88:91]
	v_mfma_f32_16x16x32_bf16 v[116:119], v[150:153], v[216:219], v[116:119]
	v_mfma_f32_16x16x32_bf16 v[84:87], v[158:161], v[216:219], v[84:87]
	v_mfma_f32_16x16x32_bf16 v[112:115], v[150:153], v[224:227], v[112:115]
	v_mfma_f32_16x16x32_bf16 v[80:83], v[158:161], v[224:227], v[80:83]
	s_setprio 0
	s_setprio 1
	v_mfma_f32_16x16x32_bf16 v[60:63], v[180:183], v[196:199], v[60:63]
	v_mfma_f32_16x16x32_bf16 v[28:31], v[188:191], v[196:199], v[28:31]
	v_mfma_f32_16x16x32_bf16 v[56:59], v[180:183], v[204:207], v[56:59]
	v_mfma_f32_16x16x32_bf16 v[24:27], v[188:191], v[204:207], v[24:27]
	v_mfma_f32_16x16x32_bf16 v[52:55], v[180:183], v[212:215], v[52:55]
	v_mfma_f32_16x16x32_bf16 v[20:23], v[188:191], v[212:215], v[20:23]
	v_mfma_f32_16x16x32_bf16 v[48:51], v[180:183], v[220:223], v[48:51]
	v_mfma_f32_16x16x32_bf16 v[16:19], v[188:191], v[220:223], v[16:19]
	s_setprio 0
	s_setprio 1
	v_mfma_f32_16x16x32_bf16 v[60:63], v[184:187], v[200:203], v[60:63]
	v_mfma_f32_16x16x32_bf16 v[28:31], v[192:195], v[200:203], v[28:31]
	v_mfma_f32_16x16x32_bf16 v[56:59], v[184:187], v[208:211], v[56:59]
	v_mfma_f32_16x16x32_bf16 v[24:27], v[192:195], v[208:211], v[24:27]
	v_mfma_f32_16x16x32_bf16 v[52:55], v[184:187], v[216:219], v[52:55]
	v_mfma_f32_16x16x32_bf16 v[20:23], v[192:195], v[216:219], v[20:23]
	v_mfma_f32_16x16x32_bf16 v[48:51], v[184:187], v[224:227], v[48:51]
	v_mfma_f32_16x16x32_bf16 v[16:19], v[192:195], v[224:227], v[16:19]
	s_barrier
; #define PG8_STAGE(bufoff, gbase, voff) do { _Pragma("unroll") for (int _i = 0; _i < 2; ++_i) \
;         __builtin_amdgcn_global_load_lds((const unsigned*)((const char*)(gbase) + (voff)[_i]), (LAS unsigned*)(lds + (bufoff) + ldsw + _i * 8192), 16, 0, 0); } while (0)
; #define PG8_LDA(dst, b, h) do { _Pragma("unroll") for (int m = 0; m < 4; ++m) _Pragma("unroll") for (int k = 0; k < 2; ++k) dst[m][k] = *(const LAS bf16x8*)(lds + PG8_SA(b, h) + aoff + m * 2048 + k * 1024); } while (0)
; #define PG8_MMA(ai, bj, At, Bt) do { __builtin_amdgcn_s_setprio(1); _Pragma("unroll") for (int m = 0; m < 4; ++m) _Pragma("unroll") for (int n = 0; n < 2; ++n) _Pragma("unroll") for (int k = 0; k < 2; ++k) \
;         acc[ai][bj][m][n] = __builtin_amdgcn_mfma_f32_16x16x32_bf16(Bt[n][k], At[m][k], acc[ai][bj][m][n], 0, 0, 0); __builtin_amdgcn_s_setprio(0); } while (0)
; #define PG8_WAIT_V(n) asm volatile("s_waitcnt vmcnt(" #n ")" ::: "memory")
; #define PG8_WAIT_L(n) asm volatile("s_waitcnt lgkmcnt(" #n ")" ::: "memory")
; #define PG8_BAR __builtin_amdgcn_s_barrier()
; #define PG8_SCHED __builtin_amdgcn_sched_barrier(0)
; template <class Epi, class Sched>
; __device__ __forceinline__ void gemm_phase(LAS unsigned char* lds, const int K, const Sched& S, const Epi& E) {
;     ...
;             PG8_LDA(At, 1, 1); PG8_STAGE(PG8_SB(1, 0), b3, voffB); PG8_STAGE(PG8_SB(1, 1), b3 + hstep, voffB); PG8_STAGE(PG8_SA(1, 0), a3, voffA);
;             PG8_WAIT_V(8); PG8_WAIT_L(0); PG8_BAR; PG8_MMA(1, 0, At, B0); PG8_MMA(1, 1, At, B1); PG8_BAR; PG8_SCHED;
;         }
;         if (wr == 0) PG8_BAR;
	s_setprio 0
	s_add_i32 s8, s12, s60
	v_lshl_add_u64 v[162:163], v[162:163], 0, s[36:37]
	s_mov_b32 m0, s8
	ds_read_b128 v[196:199], v166 offset:49152
	ds_read_b128 v[200:203], v166 offset:50176
	ds_read_b128 v[204:207], v166 offset:51200
	ds_read_b128 v[208:211], v166 offset:52224
	ds_read_b128 v[212:215], v166 offset:53248
	ds_read_b128 v[216:219], v166 offset:54272
	ds_read_b128 v[220:223], v166 offset:55296
	ds_read_b128 v[224:227], v166 offset:56320
	global_load_lds_dwordx4 v[162:163], off
	s_add_i32 m0, s8, 0x2000
	s_add_u32 s8, s54, 0xb0080
	v_lshl_add_u64 v[162:163], v[228:229], 0, s[36:37]
	s_addc_u32 s9, s55, 0
	s_add_i32 s12, s14, s60
	global_load_lds_dwordx4 v[162:163], off
	v_lshl_add_u64 v[162:163], s[8:9], 0, v[128:129]
	s_mov_b32 m0, s12
	s_nop 0
	global_load_lds_dwordx4 v[162:163], off
	v_lshl_add_u64 v[162:163], s[8:9], 0, v[138:139]
	s_add_i32 m0, s12, 0x2000
	s_nop 0
	global_load_lds_dwordx4 v[162:163], off
	v_lshl_add_u64 v[162:163], v[230:231], 0, s[36:37]
	s_mov_b32 m0, s68
	s_nop 0
	global_load_lds_dwordx4 v[162:163], off
	v_lshl_add_u64 v[162:163], v[232:233], 0, s[36:37]
	s_mov_b32 m0, s69
	s_nop 0
	global_load_lds_dwordx4 v[162:163], off
	s_waitcnt vmcnt(8)
	s_waitcnt lgkmcnt(0)
	s_setprio 1
	s_barrier
	v_mfma_f32_16x16x32_bf16 v[108:111], v[146:149], v[196:199], v[108:111]
	v_mfma_f32_16x16x32_bf16 v[76:79], v[154:157], v[196:199], v[76:79]
	v_mfma_f32_16x16x32_bf16 v[104:107], v[146:149], v[204:207], v[104:107]
	v_mfma_f32_16x16x32_bf16 v[72:75], v[154:157], v[204:207], v[72:75]
	v_mfma_f32_16x16x32_bf16 v[100:103], v[146:149], v[212:215], v[100:103]
	v_mfma_f32_16x16x32_bf16 v[68:71], v[154:157], v[212:215], v[68:71]
	v_mfma_f32_16x16x32_bf16 v[96:99], v[146:149], v[220:223], v[96:99]
	v_mfma_f32_16x16x32_bf16 v[64:67], v[154:157], v[220:223], v[64:67]
	s_setprio 0
	s_setprio 1
	v_mfma_f32_16x16x32_bf16 v[108:111], v[150:153], v[200:203], v[108:111]
	v_mfma_f32_16x16x32_bf16 v[76:79], v[158:161], v[200:203], v[76:79]
	v_mfma_f32_16x16x32_bf16 v[104:107], v[150:153], v[208:211], v[104:107]
	v_mfma_f32_16x16x32_bf16 v[72:75], v[158:161], v[208:211], v[72:75]
	v_mfma_f32_16x16x32_bf16 v[100:103], v[150:153], v[216:219], v[100:103]
	v_mfma_f32_16x16x32_bf16 v[68:71], v[158:161], v[216:219], v[68:71]
	v_mfma_f32_16x16x32_bf16 v[96:99], v[150:153], v[224:227], v[96:99]
	v_mfma_f32_16x16x32_bf16 v[64:67], v[158:161], v[224:227], v[64:67]
	s_setprio 0
	s_setprio 1
	v_mfma_f32_16x16x32_bf16 v[44:47], v[180:183], v[196:199], v[44:47]
	v_mfma_f32_16x16x32_bf16 v[12:15], v[188:191], v[196:199], v[12:15]
	v_mfma_f32_16x16x32_bf16 v[40:43], v[180:183], v[204:207], v[40:43]
	v_mfma_f32_16x16x32_bf16 v[8:11], v[188:191], v[204:207], v[8:11]
	v_mfma_f32_16x16x32_bf16 v[36:39], v[180:183], v[212:215], v[36:39]
	v_mfma_f32_16x16x32_bf16 v[4:7], v[188:191], v[212:215], v[4:7]
	v_mfma_f32_16x16x32_bf16 v[32:35], v[180:183], v[220:223], v[32:35]
	v_mfma_f32_16x16x32_bf16 v[0:3], v[188:191], v[220:223], v[0:3]
	s_setprio 0
	s_setprio 1
	v_mfma_f32_16x16x32_bf16 v[44:47], v[184:187], v[200:203], v[44:47]
	v_mfma_f32_16x16x32_bf16 v[12:15], v[192:195], v[200:203], v[12:15]
	v_mfma_f32_16x16x32_bf16 v[40:43], v[184:187], v[208:211], v[40:43]
	v_mfma_f32_16x16x32_bf16 v[8:11], v[192:195], v[208:211], v[8:11]
	v_mfma_f32_16x16x32_bf16 v[36:39], v[184:187], v[216:219], v[36:39]
	v_mfma_f32_16x16x32_bf16 v[4:7], v[192:195], v[216:219], v[4:7]
	v_mfma_f32_16x16x32_bf16 v[32:35], v[184:187], v[224:227], v[32:35]
	v_mfma_f32_16x16x32_bf16 v[0:3], v[192:195], v[224:227], v[0:3]
	s_barrier
	s_setprio 0
	s_add_u32 s10, s10, 0x100
	s_addc_u32 s11, s11, 0
	s_cmp_ge_i32 s13, s51
	s_mov_b64 s[8:9], s[52:53]
	s_mov_b32 s12, s13
	s_cbranch_scc0 .LBB0_1073
	s_and_b64 vcc, exec, s[40:41]
	s_cbranch_vccz .LBB0_1076
